# batched the 16 serialized xold epilogue loads in out-proj and down into one prefetch block with counted waits
# baseline (speedup 1.0000x reference)
; __device__ __forceinline__ u32x4 pack8(const f32x4 a, const f32x4 b) { u32x4 w; w.x = cvt_pk(a[0], a[1]); w.y = cvt_pk(a[2], a[3]); w.z = cvt_pk(b[0], b[1]); w.w = cvt_pk(b[2], b[3]); return w; }
; __device__ __forceinline__ f32x4 sigm4(f32x4 v) { f32x4 o; o[0] = sigm(v[0]); o[1] = sigm(v[1]); o[2] = sigm(v[2]); o[3] = sigm(v[3]); return o; }
; __device__ __forceinline__ float sq4(f32x4 v) { return (v[0] * v[0] + v[1] * v[1]) + (v[2] * v[2] + v[3] * v[3]); }
; #define EP_ROWLOOP for (int ai = 0; ai < 2; ++ai) _Pragma("unroll") for (int m = 0; m < 4; ++m)
;     __device__ __forceinline__ void operator()(const f32x4 (&acc)[2][2][4][2], const Unit& u, int wr, int wc, int fr, int fq) const {
;     ...
;         EP_ROWLOOP { EpFence fence_{(m & (EPB - 1)) == EPB - 1};
;             const int row = rowb + ai * 128 + m * 16;
;             float rs = 1.0f; if constexpr (MODE == 1) rs = rs_get<32>(rc, ssin, u.pm, wr * 64 + fr + ai * 128 + m * 16, fq, 1.0f / 2048.0f, 1e-6f);
;             float s = 0.f;
; #pragma unroll
;             for (int bj = 0; bj < 2; ++bj) {
;                 const size_t off = (size_t)row * 2048 + cb + bj * 128;
;                 f32x4 v0 = acc[ai][bj][m][0], v1 = acc[ai][bj][m][1], x0, x1;
;                 if constexpr (MODE == 1) { f32x4 e0, e1; unpack8(*(const u32x4*)(e + off), e0, e1); v0 = sigm4(v0 * rs) * e0; v1 = sigm4(v1 * rs) * e1; }
;                 unpack8(*(const u32x4*)(xold + off), x0, x1);
;                 v0 += x0; v1 += x1;
;                 *(u32x4*)(xnew + off) = pack8(v0, v1);
;                 s += sq4(v0) + sq4(v1);
;             }
;             s += __shfl_xor(s, 16); s += __shfl_xor(s, 32);
;             if (fq == 0) ssout[(size_t)row * 32 + u.pn * 4 + wc] = s;
.LBB0_255:
	v_and_b32_e32 v144, 64, v190
	v_xor_b32_e32 v143, 16, v190
	v_add_u32_e32 v144, 64, v144
	v_cmp_lt_i32_e32 vcc, v143, v144
	v_lshl_add_u32 v142, s80, 8, v146
	v_lshl_or_b32 v140, s56, 8, v148
	v_cndmask_b32_e32 v143, v190, v143, vcc
	s_waitcnt vmcnt(0)
	v_lshlrev_b32_e32 v151, 2, v143
	v_xor_b32_e32 v143, 32, v190
	v_cmp_lt_i32_e32 vcc, v143, v144
	v_ashrrev_i32_e32 v141, 31, v140
	s_lshl_b32 s8, s56, 2
	v_cndmask_b32_e32 v143, v190, v143, vcc
	v_lshlrev_b32_e32 v150, 2, v143
	v_ashrrev_i32_e32 v143, 31, v142
	v_lshlrev_b64 v[144:145], 12, v[142:143]
	v_lshl_add_u64 v[144:145], s[26:27], 0, v[144:145]
	v_lshl_add_u64 v[144:145], v[140:141], 1, v[144:145]
	v_mov_b32_e32 v252, v144
	v_mov_b32_e32 v253, v145
	global_load_dwordx4 v[152:155], v[144:145], off
	global_load_dwordx4 v[192:195], v[252:253], off offset:256
	s_mov_b32 s99, 0
	s_mov_b32 s98, 0x10000
	v_lshl_add_u64 v[252:253], v[252:253], 0, s[98:99]
	global_load_dwordx4 v[196:199], v[252:253], off
	global_load_dwordx4 v[200:203], v[252:253], off offset:256
	s_mov_b32 s98, 0x10000
	v_lshl_add_u64 v[252:253], v[252:253], 0, s[98:99]
	global_load_dwordx4 v[204:207], v[252:253], off
	global_load_dwordx4 v[208:211], v[252:253], off offset:256
	s_mov_b32 s98, 0x10000
	v_lshl_add_u64 v[252:253], v[252:253], 0, s[98:99]
	global_load_dwordx4 v[212:215], v[252:253], off
	global_load_dwordx4 v[216:219], v[252:253], off offset:256
	s_mov_b32 s98, 0x50000
	v_lshl_add_u64 v[252:253], v[252:253], 0, s[98:99]
	global_load_dwordx4 v[220:223], v[252:253], off
	global_load_dwordx4 v[224:227], v[252:253], off offset:256
	s_mov_b32 s98, 0x10000
	v_lshl_add_u64 v[252:253], v[252:253], 0, s[98:99]
	global_load_dwordx4 v[228:231], v[252:253], off
	global_load_dwordx4 v[232:235], v[252:253], off offset:256
	s_mov_b32 s98, 0x10000
	v_lshl_add_u64 v[252:253], v[252:253], 0, s[98:99]
	global_load_dwordx4 v[236:239], v[252:253], off
	global_load_dwordx4 v[240:243], v[252:253], off offset:256
	s_mov_b32 s98, 0x10000
	v_lshl_add_u64 v[252:253], v[252:253], 0, s[98:99]
	global_load_dwordx4 v[244:247], v[252:253], off
	global_load_dwordx4 v[248:251], v[252:253], off offset:256
	s_ashr_i32 s9, s8, 31
	s_waitcnt vmcnt(15)
	v_lshlrev_b32_e32 v156, 16, v152
	v_and_b32_e32 v157, 0xffff0000, v152
	v_lshlrev_b32_e32 v152, 16, v153
	v_and_b32_e32 v153, 0xffff0000, v153
	v_lshlrev_b32_e32 v158, 16, v154
	v_and_b32_e32 v159, 0xffff0000, v154
	v_lshlrev_b32_e32 v154, 16, v155
	v_and_b32_e32 v155, 0xffff0000, v155
	v_pk_add_f32 v[152:153], v[124:125], v[152:153]
	v_pk_add_f32 v[156:157], v[122:123], v[156:157]
	v_pk_add_f32 v[128:129], v[128:129], v[154:155]
	v_pk_add_f32 v[126:127], v[126:127], v[158:159]
	v_cvt_pk_bf16_f32 v122, v156, v157
	v_cvt_pk_bf16_f32 v123, v152, v153
	v_cvt_pk_bf16_f32 v124, v126, v127
	v_cvt_pk_bf16_f32 v125, v128, v129
	global_store_dwordx4 v[144:145], v[122:125], off
	s_nop 1
	v_mul_f32_e32 v122, v157, v157
	v_mul_f32_e32 v123, v153, v153
	v_fmac_f32_e32 v122, v156, v156
	v_fmac_f32_e32 v123, v152, v152
	v_add_f32_e32 v122, v122, v123
	v_mul_f32_e32 v123, v127, v127
	v_mul_f32_e32 v124, v129, v129
	v_fmac_f32_e32 v123, v126, v126
	v_fmac_f32_e32 v124, v128, v128
	v_add_f32_e32 v123, v123, v124
	v_add_f32_e32 v152, v122, v123
	s_waitcnt vmcnt(15)
	v_mov_b32_e32 v122, v192
	v_mov_b32_e32 v123, v193
	v_mov_b32_e32 v124, v194
	v_mov_b32_e32 v125, v195
	v_lshlrev_b32_e32 v126, 16, v122
	v_and_b32_e32 v127, 0xffff0000, v122
	v_lshlrev_b32_e32 v122, 16, v123
	v_and_b32_e32 v123, 0xffff0000, v123
	v_lshlrev_b32_e32 v128, 16, v124
	v_and_b32_e32 v129, 0xffff0000, v124
	v_lshlrev_b32_e32 v124, 16, v125
	v_and_b32_e32 v125, 0xffff0000, v125
	v_pk_add_f32 v[120:121], v[120:121], v[122:123]
	v_pk_add_f32 v[118:119], v[118:119], v[126:127]
	v_pk_add_f32 v[122:123], v[116:117], v[124:125]
	v_pk_add_f32 v[124:125], v[114:115], v[128:129]
	v_cvt_pk_bf16_f32 v114, v118, v119
	v_cvt_pk_bf16_f32 v115, v120, v121
	v_cvt_pk_bf16_f32 v116, v124, v125
	v_cvt_pk_bf16_f32 v117, v122, v123
	global_store_dwordx4 v[144:145], v[114:117], off offset:256
	s_nop 1
	v_mul_f32_e32 v114, v119, v119
	v_mul_f32_e32 v115, v121, v121
	v_fmac_f32_e32 v114, v118, v118
	v_fmac_f32_e32 v115, v120, v120
	v_add_f32_e32 v114, v114, v115
	v_mul_f32_e32 v115, v125, v125
	v_mul_f32_e32 v116, v123, v123
	v_fmac_f32_e32 v115, v124, v124
	v_fmac_f32_e32 v116, v122, v122
	v_add_f32_e32 v115, v115, v116
	v_add_f32_e32 v114, v114, v115
	v_add_f32_e32 v114, v152, v114
	ds_bpermute_b32 v115, v151, v114
	s_waitcnt lgkmcnt(0)
	v_add_f32_e32 v114, v114, v115
	ds_bpermute_b32 v115, v150, v114
	s_and_saveexec_b64 s[10:11], s[38:39]
	s_cbranch_execz .LBB0_257
	v_lshlrev_b64 v[116:117], 7, v[142:143]
	v_lshl_add_u64 v[116:117], s[28:29], 0, v[116:117]
	v_lshl_add_u64 v[116:117], s[8:9], 2, v[116:117]
	s_lshl_b32 s56, s51, 2
	v_lshl_add_u64 v[116:117], v[116:117], 0, s[56:57]
	s_waitcnt lgkmcnt(0)
	v_add_f32_e32 v114, v114, v115
	global_store_dword v[116:117], v114, off
; __device__ __forceinline__ u32x4 pack8(const f32x4 a, const f32x4 b) { u32x4 w; w.x = cvt_pk(a[0], a[1]); w.y = cvt_pk(a[2], a[3]); w.z = cvt_pk(b[0], b[1]); w.w = cvt_pk(b[2], b[3]); return w; }
; __device__ __forceinline__ f32x4 sigm4(f32x4 v) { f32x4 o; o[0] = sigm(v[0]); o[1] = sigm(v[1]); o[2] = sigm(v[2]); o[3] = sigm(v[3]); return o; }
; __device__ __forceinline__ float sq4(f32x4 v) { return (v[0] * v[0] + v[1] * v[1]) + (v[2] * v[2] + v[3] * v[3]); }
; #define EP_ROWLOOP for (int ai = 0; ai < 2; ++ai) _Pragma("unroll") for (int m = 0; m < 4; ++m)
;     __device__ __forceinline__ void operator()(const f32x4 (&acc)[2][2][4][2], const Unit& u, int wr, int wc, int fr, int fq) const {
;     ...
;         EP_ROWLOOP { EpFence fence_{(m & (EPB - 1)) == EPB - 1};
;             const int row = rowb + ai * 128 + m * 16;
;             float rs = 1.0f; if constexpr (MODE == 1) rs = rs_get<32>(rc, ssin, u.pm, wr * 64 + fr + ai * 128 + m * 16, fq, 1.0f / 2048.0f, 1e-6f);
;             float s = 0.f;
; #pragma unroll
;             for (int bj = 0; bj < 2; ++bj) {
;                 const size_t off = (size_t)row * 2048 + cb + bj * 128;
;                 f32x4 v0 = acc[ai][bj][m][0], v1 = acc[ai][bj][m][1], x0, x1;
;                 if constexpr (MODE == 1) { f32x4 e0, e1; unpack8(*(const u32x4*)(e + off), e0, e1); v0 = sigm4(v0 * rs) * e0; v1 = sigm4(v1 * rs) * e1; }
;                 unpack8(*(const u32x4*)(xold + off), x0, x1);
;                 v0 += x0; v1 += x1;
;                 *(u32x4*)(xnew + off) = pack8(v0, v1);
;                 s += sq4(v0) + sq4(v1);
;             }
;             s += __shfl_xor(s, 16); s += __shfl_xor(s, 32);
;             if (fq == 0) ssout[(size_t)row * 32 + u.pn * 4 + wc] = s;
.LBB0_257:
	s_or_b64 exec, exec, s[10:11]
	v_or_b32_e32 v114, 16, v142
	s_waitcnt lgkmcnt(0)
	v_ashrrev_i32_e32 v115, 31, v114
	v_lshlrev_b64 v[116:117], 12, v[114:115]
	v_lshl_add_u64 v[116:117], s[26:27], 0, v[116:117]
	v_lshl_add_u64 v[120:121], v[140:141], 1, v[116:117]
	s_waitcnt vmcnt(15)
	v_mov_b32_e32 v116, v196
	v_mov_b32_e32 v117, v197
	v_mov_b32_e32 v118, v198
	v_mov_b32_e32 v119, v199
	v_lshlrev_b32_e32 v122, 16, v116
	v_and_b32_e32 v123, 0xffff0000, v116
	v_lshlrev_b32_e32 v116, 16, v117
	v_and_b32_e32 v117, 0xffff0000, v117
	v_lshlrev_b32_e32 v124, 16, v118
	v_and_b32_e32 v125, 0xffff0000, v118
	v_lshlrev_b32_e32 v118, 16, v119
	v_and_b32_e32 v119, 0xffff0000, v119
	v_pk_add_f32 v[112:113], v[112:113], v[116:117]
	v_pk_add_f32 v[110:111], v[110:111], v[122:123]
	v_pk_add_f32 v[116:117], v[108:109], v[118:119]
	v_pk_add_f32 v[118:119], v[106:107], v[124:125]
	v_cvt_pk_bf16_f32 v106, v110, v111
	v_cvt_pk_bf16_f32 v107, v112, v113
	v_cvt_pk_bf16_f32 v108, v118, v119
	v_cvt_pk_bf16_f32 v109, v116, v117
	global_store_dwordx4 v[120:121], v[106:109], off
	s_nop 1
	v_mul_f32_e32 v106, v111, v111
	v_mul_f32_e32 v107, v113, v113
	v_fmac_f32_e32 v106, v110, v110
	v_fmac_f32_e32 v107, v112, v112
	v_add_f32_e32 v106, v106, v107
	v_mul_f32_e32 v107, v119, v119
	v_mul_f32_e32 v108, v117, v117
	v_fmac_f32_e32 v107, v118, v118
	v_fmac_f32_e32 v108, v116, v116
	v_add_f32_e32 v107, v107, v108
	v_add_f32_e32 v116, v106, v107
	s_waitcnt vmcnt(15)
	v_mov_b32_e32 v106, v200
	v_mov_b32_e32 v107, v201
	v_mov_b32_e32 v108, v202
	v_mov_b32_e32 v109, v203
	v_lshlrev_b32_e32 v110, 16, v106
	v_and_b32_e32 v111, 0xffff0000, v106
	v_lshlrev_b32_e32 v106, 16, v107
	v_and_b32_e32 v107, 0xffff0000, v107
	v_lshlrev_b32_e32 v112, 16, v108
	v_and_b32_e32 v113, 0xffff0000, v108
	v_lshlrev_b32_e32 v108, 16, v109
	v_and_b32_e32 v109, 0xffff0000, v109
	v_pk_add_f32 v[104:105], v[104:105], v[106:107]
	v_pk_add_f32 v[102:103], v[102:103], v[110:111]
	v_pk_add_f32 v[106:107], v[100:101], v[108:109]
	v_pk_add_f32 v[108:109], v[98:99], v[112:113]
	v_cvt_pk_bf16_f32 v98, v102, v103
	v_cvt_pk_bf16_f32 v99, v104, v105
	v_cvt_pk_bf16_f32 v100, v108, v109
	v_cvt_pk_bf16_f32 v101, v106, v107
	global_store_dwordx4 v[120:121], v[98:101], off offset:256
	s_nop 1
	v_mul_f32_e32 v98, v103, v103
	v_mul_f32_e32 v99, v105, v105
	v_fmac_f32_e32 v98, v102, v102
	v_fmac_f32_e32 v99, v104, v104
	v_add_f32_e32 v98, v98, v99
	v_mul_f32_e32 v99, v109, v109
	v_mul_f32_e32 v100, v107, v107
	v_fmac_f32_e32 v99, v108, v108
	v_fmac_f32_e32 v100, v106, v106
	v_add_f32_e32 v99, v99, v100
	v_add_f32_e32 v98, v98, v99
	v_add_f32_e32 v98, v116, v98
	ds_bpermute_b32 v99, v151, v98
	s_waitcnt lgkmcnt(0)
	v_add_f32_e32 v98, v98, v99
	ds_bpermute_b32 v99, v150, v98
	s_and_saveexec_b64 s[10:11], s[38:39]
	s_cbranch_execz .LBB0_259
	v_lshlrev_b64 v[100:101], 7, v[114:115]
	v_lshl_add_u64 v[100:101], s[28:29], 0, v[100:101]
	v_lshl_add_u64 v[100:101], s[8:9], 2, v[100:101]
	s_lshl_b32 s56, s51, 2
	v_lshl_add_u64 v[100:101], v[100:101], 0, s[56:57]
	s_waitcnt lgkmcnt(0)
	v_add_f32_e32 v98, v98, v99
	global_store_dword v[100:101], v98, off
.LBB0_259:
	s_or_b64 exec, exec, s[10:11]
	v_or_b32_e32 v98, 32, v142
	s_waitcnt lgkmcnt(0)
	v_ashrrev_i32_e32 v99, 31, v98
	v_lshlrev_b64 v[100:101], 12, v[98:99]
	v_lshl_add_u64 v[100:101], s[26:27], 0, v[100:101]
	v_lshl_add_u64 v[104:105], v[140:141], 1, v[100:101]
	s_waitcnt vmcnt(15)
	v_mov_b32_e32 v100, v204
	v_mov_b32_e32 v101, v205
	v_mov_b32_e32 v102, v206
	v_mov_b32_e32 v103, v207
	v_lshlrev_b32_e32 v106, 16, v100
	v_and_b32_e32 v107, 0xffff0000, v100
	v_lshlrev_b32_e32 v100, 16, v101
	v_and_b32_e32 v101, 0xffff0000, v101
	v_lshlrev_b32_e32 v108, 16, v102
	v_and_b32_e32 v109, 0xffff0000, v102
	v_lshlrev_b32_e32 v102, 16, v103
	v_and_b32_e32 v103, 0xffff0000, v103
	v_pk_add_f32 v[96:97], v[96:97], v[100:101]
	v_pk_add_f32 v[94:95], v[94:95], v[106:107]
	v_pk_add_f32 v[100:101], v[92:93], v[102:103]
	v_pk_add_f32 v[102:103], v[90:91], v[108:109]
	v_cvt_pk_bf16_f32 v90, v94, v95
	v_cvt_pk_bf16_f32 v91, v96, v97
	v_cvt_pk_bf16_f32 v92, v102, v103
	v_cvt_pk_bf16_f32 v93, v100, v101
	global_store_dwordx4 v[104:105], v[90:93], off
	s_nop 1
	v_mul_f32_e32 v90, v95, v95
	v_mul_f32_e32 v91, v97, v97
	v_fmac_f32_e32 v90, v94, v94
	v_fmac_f32_e32 v91, v96, v96
	v_add_f32_e32 v90, v90, v91
	v_mul_f32_e32 v91, v103, v103
	v_mul_f32_e32 v92, v101, v101
	v_fmac_f32_e32 v91, v102, v102
	v_fmac_f32_e32 v92, v100, v100
	v_add_f32_e32 v91, v91, v92
	v_add_f32_e32 v100, v90, v91
	s_waitcnt vmcnt(15)
	v_mov_b32_e32 v90, v208
	v_mov_b32_e32 v91, v209
	v_mov_b32_e32 v92, v210
	v_mov_b32_e32 v93, v211
	v_lshlrev_b32_e32 v94, 16, v90
	v_and_b32_e32 v95, 0xffff0000, v90
	v_lshlrev_b32_e32 v90, 16, v91
	v_and_b32_e32 v91, 0xffff0000, v91
	v_lshlrev_b32_e32 v96, 16, v92
	v_and_b32_e32 v97, 0xffff0000, v92
	v_lshlrev_b32_e32 v92, 16, v93
	v_and_b32_e32 v93, 0xffff0000, v93
	v_pk_add_f32 v[88:89], v[88:89], v[90:91]
	v_pk_add_f32 v[86:87], v[86:87], v[94:95]
	v_pk_add_f32 v[90:91], v[84:85], v[92:93]
	v_pk_add_f32 v[92:93], v[82:83], v[96:97]
	v_cvt_pk_bf16_f32 v82, v86, v87
	v_cvt_pk_bf16_f32 v83, v88, v89
	v_cvt_pk_bf16_f32 v84, v92, v93
	v_cvt_pk_bf16_f32 v85, v90, v91
	global_store_dwordx4 v[104:105], v[82:85], off offset:256
	s_nop 1
	v_mul_f32_e32 v82, v87, v87
	v_mul_f32_e32 v83, v89, v89
	v_fmac_f32_e32 v82, v86, v86
	v_fmac_f32_e32 v83, v88, v88
	v_add_f32_e32 v82, v82, v83
	v_mul_f32_e32 v83, v93, v93
	v_mul_f32_e32 v84, v91, v91
	v_fmac_f32_e32 v83, v92, v92
	v_fmac_f32_e32 v84, v90, v90
	v_add_f32_e32 v83, v83, v84
	v_add_f32_e32 v82, v82, v83
	v_add_f32_e32 v82, v100, v82
	ds_bpermute_b32 v83, v151, v82
	s_waitcnt lgkmcnt(0)
	v_add_f32_e32 v82, v82, v83
	ds_bpermute_b32 v83, v150, v82
	s_and_saveexec_b64 s[10:11], s[38:39]
	s_cbranch_execz .LBB0_261
	v_lshlrev_b64 v[84:85], 7, v[98:99]
	v_lshl_add_u64 v[84:85], s[28:29], 0, v[84:85]
	v_lshl_add_u64 v[84:85], s[8:9], 2, v[84:85]
	s_lshl_b32 s56, s51, 2
	v_lshl_add_u64 v[84:85], v[84:85], 0, s[56:57]
	s_waitcnt lgkmcnt(0)
	v_add_f32_e32 v82, v82, v83
	global_store_dword v[84:85], v82, off
; __device__ __forceinline__ u32x4 pack8(const f32x4 a, const f32x4 b) { u32x4 w; w.x = cvt_pk(a[0], a[1]); w.y = cvt_pk(a[2], a[3]); w.z = cvt_pk(b[0], b[1]); w.w = cvt_pk(b[2], b[3]); return w; }
; __device__ __forceinline__ f32x4 sigm4(f32x4 v) { f32x4 o; o[0] = sigm(v[0]); o[1] = sigm(v[1]); o[2] = sigm(v[2]); o[3] = sigm(v[3]); return o; }
; __device__ __forceinline__ float sq4(f32x4 v) { return (v[0] * v[0] + v[1] * v[1]) + (v[2] * v[2] + v[3] * v[3]); }
; #define EP_ROWLOOP for (int ai = 0; ai < 2; ++ai) _Pragma("unroll") for (int m = 0; m < 4; ++m)
;     __device__ __forceinline__ void operator()(const f32x4 (&acc)[2][2][4][2], const Unit& u, int wr, int wc, int fr, int fq) const {
;     ...
;         EP_ROWLOOP { EpFence fence_{(m & (EPB - 1)) == EPB - 1};
;             const int row = rowb + ai * 128 + m * 16;
;             float rs = 1.0f; if constexpr (MODE == 1) rs = rs_get<32>(rc, ssin, u.pm, wr * 64 + fr + ai * 128 + m * 16, fq, 1.0f / 2048.0f, 1e-6f);
;             float s = 0.f;
; #pragma unroll
;             for (int bj = 0; bj < 2; ++bj) {
;                 const size_t off = (size_t)row * 2048 + cb + bj * 128;
;                 f32x4 v0 = acc[ai][bj][m][0], v1 = acc[ai][bj][m][1], x0, x1;
;                 if constexpr (MODE == 1) { f32x4 e0, e1; unpack8(*(const u32x4*)(e + off), e0, e1); v0 = sigm4(v0 * rs) * e0; v1 = sigm4(v1 * rs) * e1; }
;                 unpack8(*(const u32x4*)(xold + off), x0, x1);
;                 v0 += x0; v1 += x1;
;                 *(u32x4*)(xnew + off) = pack8(v0, v1);
;                 s += sq4(v0) + sq4(v1);
;             }
;             s += __shfl_xor(s, 16); s += __shfl_xor(s, 32);
;             if (fq == 0) ssout[(size_t)row * 32 + u.pn * 4 + wc] = s;
.LBB0_261:
	s_or_b64 exec, exec, s[10:11]
	v_or_b32_e32 v82, 48, v142
	s_waitcnt lgkmcnt(0)
	v_ashrrev_i32_e32 v83, 31, v82
	v_lshlrev_b64 v[84:85], 12, v[82:83]
	v_lshl_add_u64 v[84:85], s[26:27], 0, v[84:85]
	v_lshl_add_u64 v[88:89], v[140:141], 1, v[84:85]
	s_waitcnt vmcnt(15)
	v_mov_b32_e32 v84, v212
	v_mov_b32_e32 v85, v213
	v_mov_b32_e32 v86, v214
	v_mov_b32_e32 v87, v215
	v_lshlrev_b32_e32 v90, 16, v84
	v_and_b32_e32 v91, 0xffff0000, v84
	v_lshlrev_b32_e32 v84, 16, v85
	v_and_b32_e32 v85, 0xffff0000, v85
	v_lshlrev_b32_e32 v92, 16, v86
	v_and_b32_e32 v93, 0xffff0000, v86
	v_lshlrev_b32_e32 v86, 16, v87
	v_and_b32_e32 v87, 0xffff0000, v87
	v_pk_add_f32 v[80:81], v[80:81], v[84:85]
	v_pk_add_f32 v[78:79], v[78:79], v[90:91]
	v_pk_add_f32 v[84:85], v[76:77], v[86:87]
	v_pk_add_f32 v[86:87], v[74:75], v[92:93]
	v_cvt_pk_bf16_f32 v74, v78, v79
	v_cvt_pk_bf16_f32 v75, v80, v81
	v_cvt_pk_bf16_f32 v76, v86, v87
	v_cvt_pk_bf16_f32 v77, v84, v85
	global_store_dwordx4 v[88:89], v[74:77], off
	s_nop 1
	v_mul_f32_e32 v74, v79, v79
	v_mul_f32_e32 v75, v81, v81
	v_fmac_f32_e32 v74, v78, v78
	v_fmac_f32_e32 v75, v80, v80
	v_add_f32_e32 v74, v74, v75
	v_mul_f32_e32 v75, v87, v87
	v_mul_f32_e32 v76, v85, v85
	v_fmac_f32_e32 v75, v86, v86
	v_fmac_f32_e32 v76, v84, v84
	v_add_f32_e32 v75, v75, v76
	v_add_f32_e32 v84, v74, v75
	s_waitcnt vmcnt(15)
	v_mov_b32_e32 v74, v216
	v_mov_b32_e32 v75, v217
	v_mov_b32_e32 v76, v218
	v_mov_b32_e32 v77, v219
	v_lshlrev_b32_e32 v78, 16, v74
	v_and_b32_e32 v79, 0xffff0000, v74
	v_lshlrev_b32_e32 v74, 16, v75
	v_and_b32_e32 v75, 0xffff0000, v75
	v_lshlrev_b32_e32 v80, 16, v76
	v_and_b32_e32 v81, 0xffff0000, v76
	v_lshlrev_b32_e32 v76, 16, v77
	v_and_b32_e32 v77, 0xffff0000, v77
	v_pk_add_f32 v[72:73], v[72:73], v[74:75]
	v_pk_add_f32 v[70:71], v[70:71], v[78:79]
	v_pk_add_f32 v[74:75], v[68:69], v[76:77]
	v_pk_add_f32 v[76:77], v[66:67], v[80:81]
	v_cvt_pk_bf16_f32 v66, v70, v71
	v_cvt_pk_bf16_f32 v67, v72, v73
	v_cvt_pk_bf16_f32 v68, v76, v77
	v_cvt_pk_bf16_f32 v69, v74, v75
	global_store_dwordx4 v[88:89], v[66:69], off offset:256
	s_nop 1
	v_mul_f32_e32 v66, v71, v71
	v_mul_f32_e32 v67, v73, v73
	v_fmac_f32_e32 v66, v70, v70
	v_fmac_f32_e32 v67, v72, v72
	v_add_f32_e32 v66, v66, v67
	v_mul_f32_e32 v67, v77, v77
	v_mul_f32_e32 v68, v75, v75
	v_fmac_f32_e32 v67, v76, v76
	v_fmac_f32_e32 v68, v74, v74
	v_add_f32_e32 v67, v67, v68
	v_add_f32_e32 v66, v66, v67
	v_add_f32_e32 v66, v84, v66
	ds_bpermute_b32 v67, v151, v66
	s_waitcnt lgkmcnt(0)
	v_add_f32_e32 v66, v66, v67
	ds_bpermute_b32 v67, v150, v66
	s_and_saveexec_b64 s[10:11], s[38:39]
	s_cbranch_execz .LBB0_263
	v_lshlrev_b64 v[68:69], 7, v[82:83]
	v_lshl_add_u64 v[68:69], s[28:29], 0, v[68:69]
	v_lshl_add_u64 v[68:69], s[8:9], 2, v[68:69]
	s_lshl_b32 s56, s51, 2
	v_lshl_add_u64 v[68:69], v[68:69], 0, s[56:57]
	s_waitcnt lgkmcnt(0)
	v_add_f32_e32 v66, v66, v67
	global_store_dword v[68:69], v66, off
.LBB0_263:
	s_or_b64 exec, exec, s[10:11]
	v_add_u32_e32 v66, 0x80, v142
	s_waitcnt lgkmcnt(0)
	v_ashrrev_i32_e32 v67, 31, v66
	v_lshlrev_b64 v[68:69], 12, v[66:67]
	v_lshl_add_u64 v[68:69], s[26:27], 0, v[68:69]
	v_lshl_add_u64 v[72:73], v[140:141], 1, v[68:69]
	s_waitcnt vmcnt(15)
	v_mov_b32_e32 v68, v220
	v_mov_b32_e32 v69, v221
	v_mov_b32_e32 v70, v222
	v_mov_b32_e32 v71, v223
	v_lshlrev_b32_e32 v74, 16, v68
	v_and_b32_e32 v75, 0xffff0000, v68
	v_lshlrev_b32_e32 v68, 16, v69
	v_and_b32_e32 v69, 0xffff0000, v69
	v_lshlrev_b32_e32 v76, 16, v70
	v_and_b32_e32 v77, 0xffff0000, v70
	v_lshlrev_b32_e32 v70, 16, v71
	v_and_b32_e32 v71, 0xffff0000, v71
	v_pk_add_f32 v[64:65], v[64:65], v[68:69]
	v_pk_add_f32 v[62:63], v[62:63], v[74:75]
	v_pk_add_f32 v[68:69], v[60:61], v[70:71]
	v_pk_add_f32 v[70:71], v[58:59], v[76:77]
	v_cvt_pk_bf16_f32 v58, v62, v63
	v_cvt_pk_bf16_f32 v59, v64, v65
	v_cvt_pk_bf16_f32 v60, v70, v71
	v_cvt_pk_bf16_f32 v61, v68, v69
	global_store_dwordx4 v[72:73], v[58:61], off
	s_nop 1
	v_mul_f32_e32 v58, v63, v63
	v_mul_f32_e32 v59, v65, v65
	v_fmac_f32_e32 v58, v62, v62
	v_fmac_f32_e32 v59, v64, v64
	v_add_f32_e32 v58, v58, v59
	v_mul_f32_e32 v59, v71, v71
	v_mul_f32_e32 v60, v69, v69
	v_fmac_f32_e32 v59, v70, v70
	v_fmac_f32_e32 v60, v68, v68
	v_add_f32_e32 v59, v59, v60
	v_add_f32_e32 v68, v58, v59
	s_waitcnt vmcnt(15)
	v_mov_b32_e32 v58, v224
	v_mov_b32_e32 v59, v225
	v_mov_b32_e32 v60, v226
	v_mov_b32_e32 v61, v227
	v_lshlrev_b32_e32 v62, 16, v58
	v_and_b32_e32 v63, 0xffff0000, v58
	v_lshlrev_b32_e32 v58, 16, v59
	v_and_b32_e32 v59, 0xffff0000, v59
	v_lshlrev_b32_e32 v64, 16, v60
	v_and_b32_e32 v65, 0xffff0000, v60
	v_lshlrev_b32_e32 v60, 16, v61
	v_and_b32_e32 v61, 0xffff0000, v61
	v_pk_add_f32 v[56:57], v[56:57], v[58:59]
	v_pk_add_f32 v[54:55], v[54:55], v[62:63]
	v_pk_add_f32 v[58:59], v[52:53], v[60:61]
	v_pk_add_f32 v[60:61], v[50:51], v[64:65]
	v_cvt_pk_bf16_f32 v50, v54, v55
	v_cvt_pk_bf16_f32 v51, v56, v57
	v_cvt_pk_bf16_f32 v52, v60, v61
	v_cvt_pk_bf16_f32 v53, v58, v59
	global_store_dwordx4 v[72:73], v[50:53], off offset:256
	s_nop 1
	v_mul_f32_e32 v50, v55, v55
	v_mul_f32_e32 v51, v57, v57
	v_fmac_f32_e32 v50, v54, v54
	v_fmac_f32_e32 v51, v56, v56
	v_add_f32_e32 v50, v50, v51
	v_mul_f32_e32 v51, v61, v61
	v_mul_f32_e32 v52, v59, v59
	v_fmac_f32_e32 v51, v60, v60
	v_fmac_f32_e32 v52, v58, v58
	v_add_f32_e32 v51, v51, v52
	v_add_f32_e32 v50, v50, v51
	v_add_f32_e32 v50, v68, v50
	ds_bpermute_b32 v51, v151, v50
	s_waitcnt lgkmcnt(0)
	v_add_f32_e32 v50, v50, v51
	ds_bpermute_b32 v51, v150, v50
	s_and_saveexec_b64 s[10:11], s[38:39]
	s_cbranch_execz .LBB0_265
	v_lshlrev_b64 v[52:53], 7, v[66:67]
	v_lshl_add_u64 v[52:53], s[28:29], 0, v[52:53]
	v_lshl_add_u64 v[52:53], s[8:9], 2, v[52:53]
	s_lshl_b32 s56, s51, 2
	v_lshl_add_u64 v[52:53], v[52:53], 0, s[56:57]
	s_waitcnt lgkmcnt(0)
	v_add_f32_e32 v50, v50, v51
	global_store_dword v[52:53], v50, off
; __device__ __forceinline__ u32x4 pack8(const f32x4 a, const f32x4 b) { u32x4 w; w.x = cvt_pk(a[0], a[1]); w.y = cvt_pk(a[2], a[3]); w.z = cvt_pk(b[0], b[1]); w.w = cvt_pk(b[2], b[3]); return w; }
; __device__ __forceinline__ f32x4 sigm4(f32x4 v) { f32x4 o; o[0] = sigm(v[0]); o[1] = sigm(v[1]); o[2] = sigm(v[2]); o[3] = sigm(v[3]); return o; }
; __device__ __forceinline__ float sq4(f32x4 v) { return (v[0] * v[0] + v[1] * v[1]) + (v[2] * v[2] + v[3] * v[3]); }
; #define EP_ROWLOOP for (int ai = 0; ai < 2; ++ai) _Pragma("unroll") for (int m = 0; m < 4; ++m)
;     __device__ __forceinline__ void operator()(const f32x4 (&acc)[2][2][4][2], const Unit& u, int wr, int wc, int fr, int fq) const {
;     ...
;         EP_ROWLOOP { EpFence fence_{(m & (EPB - 1)) == EPB - 1};
;             const int row = rowb + ai * 128 + m * 16;
;             float rs = 1.0f; if constexpr (MODE == 1) rs = rs_get<32>(rc, ssin, u.pm, wr * 64 + fr + ai * 128 + m * 16, fq, 1.0f / 2048.0f, 1e-6f);
;             float s = 0.f;
; #pragma unroll
;             for (int bj = 0; bj < 2; ++bj) {
;                 const size_t off = (size_t)row * 2048 + cb + bj * 128;
;                 f32x4 v0 = acc[ai][bj][m][0], v1 = acc[ai][bj][m][1], x0, x1;
;                 if constexpr (MODE == 1) { f32x4 e0, e1; unpack8(*(const u32x4*)(e + off), e0, e1); v0 = sigm4(v0 * rs) * e0; v1 = sigm4(v1 * rs) * e1; }
;                 unpack8(*(const u32x4*)(xold + off), x0, x1);
;                 v0 += x0; v1 += x1;
;                 *(u32x4*)(xnew + off) = pack8(v0, v1);
;                 s += sq4(v0) + sq4(v1);
;             }
;             s += __shfl_xor(s, 16); s += __shfl_xor(s, 32);
;             if (fq == 0) ssout[(size_t)row * 32 + u.pn * 4 + wc] = s;
.LBB0_265:
	s_or_b64 exec, exec, s[10:11]
	v_add_u32_e32 v50, 0x90, v142
	s_waitcnt lgkmcnt(0)
	v_ashrrev_i32_e32 v51, 31, v50
	v_lshlrev_b64 v[52:53], 12, v[50:51]
	v_lshl_add_u64 v[52:53], s[26:27], 0, v[52:53]
	v_lshl_add_u64 v[56:57], v[140:141], 1, v[52:53]
	s_waitcnt vmcnt(15)
	v_mov_b32_e32 v52, v228
	v_mov_b32_e32 v53, v229
	v_mov_b32_e32 v54, v230
	v_mov_b32_e32 v55, v231
	v_lshlrev_b32_e32 v58, 16, v52
	v_and_b32_e32 v59, 0xffff0000, v52
	v_lshlrev_b32_e32 v52, 16, v53
	v_and_b32_e32 v53, 0xffff0000, v53
	v_lshlrev_b32_e32 v60, 16, v54
	v_and_b32_e32 v61, 0xffff0000, v54
	v_lshlrev_b32_e32 v54, 16, v55
	v_and_b32_e32 v55, 0xffff0000, v55
	v_pk_add_f32 v[48:49], v[48:49], v[52:53]
	v_pk_add_f32 v[46:47], v[46:47], v[58:59]
	v_pk_add_f32 v[52:53], v[44:45], v[54:55]
	v_pk_add_f32 v[54:55], v[42:43], v[60:61]
	v_cvt_pk_bf16_f32 v42, v46, v47
	v_cvt_pk_bf16_f32 v43, v48, v49
	v_cvt_pk_bf16_f32 v44, v54, v55
	v_cvt_pk_bf16_f32 v45, v52, v53
	global_store_dwordx4 v[56:57], v[42:45], off
	s_nop 1
	v_mul_f32_e32 v42, v47, v47
	v_mul_f32_e32 v43, v49, v49
	v_fmac_f32_e32 v42, v46, v46
	v_fmac_f32_e32 v43, v48, v48
	v_add_f32_e32 v42, v42, v43
	v_mul_f32_e32 v43, v55, v55
	v_mul_f32_e32 v44, v53, v53
	v_fmac_f32_e32 v43, v54, v54
	v_fmac_f32_e32 v44, v52, v52
	v_add_f32_e32 v43, v43, v44
	v_add_f32_e32 v52, v42, v43
	s_waitcnt vmcnt(15)
	v_mov_b32_e32 v42, v232
	v_mov_b32_e32 v43, v233
	v_mov_b32_e32 v44, v234
	v_mov_b32_e32 v45, v235
	v_lshlrev_b32_e32 v46, 16, v42
	v_and_b32_e32 v47, 0xffff0000, v42
	v_lshlrev_b32_e32 v42, 16, v43
	v_and_b32_e32 v43, 0xffff0000, v43
	v_lshlrev_b32_e32 v48, 16, v44
	v_and_b32_e32 v49, 0xffff0000, v44
	v_lshlrev_b32_e32 v44, 16, v45
	v_and_b32_e32 v45, 0xffff0000, v45
	v_pk_add_f32 v[40:41], v[40:41], v[42:43]
	v_pk_add_f32 v[38:39], v[38:39], v[46:47]
	v_pk_add_f32 v[42:43], v[36:37], v[44:45]
	v_pk_add_f32 v[44:45], v[34:35], v[48:49]
	v_cvt_pk_bf16_f32 v34, v38, v39
	v_cvt_pk_bf16_f32 v35, v40, v41
	v_cvt_pk_bf16_f32 v36, v44, v45
	v_cvt_pk_bf16_f32 v37, v42, v43
	global_store_dwordx4 v[56:57], v[34:37], off offset:256
	s_nop 1
	v_mul_f32_e32 v34, v39, v39
	v_mul_f32_e32 v35, v41, v41
	v_fmac_f32_e32 v34, v38, v38
	v_fmac_f32_e32 v35, v40, v40
	v_add_f32_e32 v34, v34, v35
	v_mul_f32_e32 v35, v45, v45
	v_mul_f32_e32 v36, v43, v43
	v_fmac_f32_e32 v35, v44, v44
	v_fmac_f32_e32 v36, v42, v42
	v_add_f32_e32 v35, v35, v36
	v_add_f32_e32 v34, v34, v35
	v_add_f32_e32 v34, v52, v34
	ds_bpermute_b32 v35, v151, v34
	s_waitcnt lgkmcnt(0)
	v_add_f32_e32 v34, v34, v35
	ds_bpermute_b32 v35, v150, v34
	s_and_saveexec_b64 s[10:11], s[38:39]
	s_cbranch_execz .LBB0_267
	v_lshlrev_b64 v[36:37], 7, v[50:51]
	v_lshl_add_u64 v[36:37], s[28:29], 0, v[36:37]
	v_lshl_add_u64 v[36:37], s[8:9], 2, v[36:37]
	s_lshl_b32 s56, s51, 2
	v_lshl_add_u64 v[36:37], v[36:37], 0, s[56:57]
	s_waitcnt lgkmcnt(0)
	v_add_f32_e32 v34, v34, v35
	global_store_dword v[36:37], v34, off
; __device__ __forceinline__ u32x4 pack8(const f32x4 a, const f32x4 b) { u32x4 w; w.x = cvt_pk(a[0], a[1]); w.y = cvt_pk(a[2], a[3]); w.z = cvt_pk(b[0], b[1]); w.w = cvt_pk(b[2], b[3]); return w; }
; __device__ __forceinline__ f32x4 sigm4(f32x4 v) { f32x4 o; o[0] = sigm(v[0]); o[1] = sigm(v[1]); o[2] = sigm(v[2]); o[3] = sigm(v[3]); return o; }
; __device__ __forceinline__ float sq4(f32x4 v) { return (v[0] * v[0] + v[1] * v[1]) + (v[2] * v[2] + v[3] * v[3]); }
; #define EP_ROWLOOP for (int ai = 0; ai < 2; ++ai) _Pragma("unroll") for (int m = 0; m < 4; ++m)
;     __device__ __forceinline__ void operator()(const f32x4 (&acc)[2][2][4][2], const Unit& u, int wr, int wc, int fr, int fq) const {
;     ...
;         EP_ROWLOOP { EpFence fence_{(m & (EPB - 1)) == EPB - 1};
;             const int row = rowb + ai * 128 + m * 16;
;             float rs = 1.0f; if constexpr (MODE == 1) rs = rs_get<32>(rc, ssin, u.pm, wr * 64 + fr + ai * 128 + m * 16, fq, 1.0f / 2048.0f, 1e-6f);
;             float s = 0.f;
; #pragma unroll
;             for (int bj = 0; bj < 2; ++bj) {
;                 const size_t off = (size_t)row * 2048 + cb + bj * 128;
;                 f32x4 v0 = acc[ai][bj][m][0], v1 = acc[ai][bj][m][1], x0, x1;
;                 if constexpr (MODE == 1) { f32x4 e0, e1; unpack8(*(const u32x4*)(e + off), e0, e1); v0 = sigm4(v0 * rs) * e0; v1 = sigm4(v1 * rs) * e1; }
;                 unpack8(*(const u32x4*)(xold + off), x0, x1);
;                 v0 += x0; v1 += x1;
;                 *(u32x4*)(xnew + off) = pack8(v0, v1);
;                 s += sq4(v0) + sq4(v1);
;             }
;             s += __shfl_xor(s, 16); s += __shfl_xor(s, 32);
;             if (fq == 0) ssout[(size_t)row * 32 + u.pn * 4 + wc] = s;
.LBB0_267:
	s_or_b64 exec, exec, s[10:11]
	v_add_u32_e32 v34, 0xa0, v142
	s_waitcnt lgkmcnt(0)
	v_ashrrev_i32_e32 v35, 31, v34
	v_lshlrev_b64 v[36:37], 12, v[34:35]
	v_lshl_add_u64 v[36:37], s[26:27], 0, v[36:37]
	v_lshl_add_u64 v[40:41], v[140:141], 1, v[36:37]
	s_waitcnt vmcnt(15)
	v_mov_b32_e32 v36, v236
	v_mov_b32_e32 v37, v237
	v_mov_b32_e32 v38, v238
	v_mov_b32_e32 v39, v239
	v_lshlrev_b32_e32 v42, 16, v36
	v_and_b32_e32 v43, 0xffff0000, v36
	v_lshlrev_b32_e32 v36, 16, v37
	v_and_b32_e32 v37, 0xffff0000, v37
	v_lshlrev_b32_e32 v44, 16, v38
	v_and_b32_e32 v45, 0xffff0000, v38
	v_lshlrev_b32_e32 v38, 16, v39
	v_and_b32_e32 v39, 0xffff0000, v39
	v_pk_add_f32 v[32:33], v[32:33], v[36:37]
	v_pk_add_f32 v[30:31], v[30:31], v[42:43]
	v_pk_add_f32 v[36:37], v[28:29], v[38:39]
	v_pk_add_f32 v[38:39], v[26:27], v[44:45]
	v_cvt_pk_bf16_f32 v26, v30, v31
	v_cvt_pk_bf16_f32 v27, v32, v33
	v_cvt_pk_bf16_f32 v28, v38, v39
	v_cvt_pk_bf16_f32 v29, v36, v37
	global_store_dwordx4 v[40:41], v[26:29], off
	s_nop 1
	v_mul_f32_e32 v26, v31, v31
	v_mul_f32_e32 v27, v33, v33
	v_fmac_f32_e32 v26, v30, v30
	v_fmac_f32_e32 v27, v32, v32
	v_add_f32_e32 v26, v26, v27
	v_mul_f32_e32 v27, v39, v39
	v_mul_f32_e32 v28, v37, v37
	v_fmac_f32_e32 v27, v38, v38
	v_fmac_f32_e32 v28, v36, v36
	v_add_f32_e32 v27, v27, v28
	v_add_f32_e32 v36, v26, v27
	s_waitcnt vmcnt(15)
	v_mov_b32_e32 v26, v240
	v_mov_b32_e32 v27, v241
	v_mov_b32_e32 v28, v242
	v_mov_b32_e32 v29, v243
	v_lshlrev_b32_e32 v30, 16, v26
	v_and_b32_e32 v31, 0xffff0000, v26
	v_lshlrev_b32_e32 v26, 16, v27
	v_and_b32_e32 v27, 0xffff0000, v27
	v_lshlrev_b32_e32 v32, 16, v28
	v_and_b32_e32 v33, 0xffff0000, v28
	v_lshlrev_b32_e32 v28, 16, v29
	v_and_b32_e32 v29, 0xffff0000, v29
	v_pk_add_f32 v[24:25], v[24:25], v[26:27]
	v_pk_add_f32 v[22:23], v[22:23], v[30:31]
	v_pk_add_f32 v[26:27], v[20:21], v[28:29]
	v_pk_add_f32 v[28:29], v[18:19], v[32:33]
	v_cvt_pk_bf16_f32 v18, v22, v23
	v_cvt_pk_bf16_f32 v19, v24, v25
	v_cvt_pk_bf16_f32 v20, v28, v29
	v_cvt_pk_bf16_f32 v21, v26, v27
	global_store_dwordx4 v[40:41], v[18:21], off offset:256
	s_nop 1
	v_mul_f32_e32 v18, v23, v23
	v_mul_f32_e32 v19, v25, v25
	v_fmac_f32_e32 v18, v22, v22
	v_fmac_f32_e32 v19, v24, v24
	v_add_f32_e32 v18, v18, v19
	v_mul_f32_e32 v19, v29, v29
	v_mul_f32_e32 v20, v27, v27
	v_fmac_f32_e32 v19, v28, v28
	v_fmac_f32_e32 v20, v26, v26
	v_add_f32_e32 v19, v19, v20
	v_add_f32_e32 v18, v18, v19
	v_add_f32_e32 v18, v36, v18
	ds_bpermute_b32 v19, v151, v18
	s_waitcnt lgkmcnt(0)
	v_add_f32_e32 v18, v18, v19
	ds_bpermute_b32 v19, v150, v18
	s_and_saveexec_b64 s[10:11], s[38:39]
	s_cbranch_execz .LBB0_269
	v_lshlrev_b64 v[20:21], 7, v[34:35]
	v_lshl_add_u64 v[20:21], s[28:29], 0, v[20:21]
	v_lshl_add_u64 v[20:21], s[8:9], 2, v[20:21]
	s_lshl_b32 s56, s51, 2
	v_lshl_add_u64 v[20:21], v[20:21], 0, s[56:57]
	s_waitcnt lgkmcnt(0)
	v_add_f32_e32 v18, v18, v19
	global_store_dword v[20:21], v18, off
.LBB0_269:
	s_or_b64 exec, exec, s[10:11]
	v_add_u32_e32 v18, 0xb0, v142
	s_waitcnt lgkmcnt(0)
	v_ashrrev_i32_e32 v19, 31, v18
	v_lshlrev_b64 v[20:21], 12, v[18:19]
	v_lshl_add_u64 v[20:21], s[26:27], 0, v[20:21]
	v_lshl_add_u64 v[24:25], v[140:141], 1, v[20:21]
	s_waitcnt vmcnt(15)
	v_mov_b32_e32 v20, v244
	v_mov_b32_e32 v21, v245
	v_mov_b32_e32 v22, v246
	v_mov_b32_e32 v23, v247
	v_lshlrev_b32_e32 v26, 16, v20
	v_and_b32_e32 v27, 0xffff0000, v20
	v_lshlrev_b32_e32 v20, 16, v21
	v_and_b32_e32 v21, 0xffff0000, v21
	v_lshlrev_b32_e32 v28, 16, v22
	v_and_b32_e32 v29, 0xffff0000, v22
	v_lshlrev_b32_e32 v22, 16, v23
	v_and_b32_e32 v23, 0xffff0000, v23
	v_pk_add_f32 v[16:17], v[16:17], v[20:21]
	v_pk_add_f32 v[14:15], v[14:15], v[26:27]
	v_pk_add_f32 v[20:21], v[12:13], v[22:23]
	v_pk_add_f32 v[22:23], v[10:11], v[28:29]
	v_cvt_pk_bf16_f32 v10, v14, v15
	v_cvt_pk_bf16_f32 v11, v16, v17
	v_cvt_pk_bf16_f32 v12, v22, v23
	v_cvt_pk_bf16_f32 v13, v20, v21
	global_store_dwordx4 v[24:25], v[10:13], off
	s_nop 1
	v_mul_f32_e32 v10, v15, v15
	v_mul_f32_e32 v11, v17, v17
	v_fmac_f32_e32 v10, v14, v14
	v_fmac_f32_e32 v11, v16, v16
	v_add_f32_e32 v10, v10, v11
	v_mul_f32_e32 v11, v23, v23
	v_mul_f32_e32 v12, v21, v21
	v_fmac_f32_e32 v11, v22, v22
	v_fmac_f32_e32 v12, v20, v20
	v_add_f32_e32 v11, v11, v12
	v_add_f32_e32 v20, v10, v11
	s_waitcnt vmcnt(15)
	v_mov_b32_e32 v10, v248
	v_mov_b32_e32 v11, v249
	v_mov_b32_e32 v12, v250
	v_mov_b32_e32 v13, v251
	v_lshlrev_b32_e32 v14, 16, v10
	v_and_b32_e32 v15, 0xffff0000, v10
	v_lshlrev_b32_e32 v10, 16, v11
	v_and_b32_e32 v11, 0xffff0000, v11
	v_lshlrev_b32_e32 v16, 16, v12
	v_and_b32_e32 v17, 0xffff0000, v12
	v_lshlrev_b32_e32 v12, 16, v13
	v_and_b32_e32 v13, 0xffff0000, v13
	v_pk_add_f32 v[8:9], v[8:9], v[10:11]
	v_pk_add_f32 v[6:7], v[6:7], v[14:15]
	v_pk_add_f32 v[10:11], v[4:5], v[12:13]
	v_pk_add_f32 v[12:13], v[2:3], v[16:17]
	v_cvt_pk_bf16_f32 v2, v6, v7
	v_cvt_pk_bf16_f32 v3, v8, v9
	v_cvt_pk_bf16_f32 v4, v12, v13
	v_cvt_pk_bf16_f32 v5, v10, v11
	global_store_dwordx4 v[24:25], v[2:5], off offset:256
	s_nop 1
	v_mul_f32_e32 v2, v7, v7
	v_mul_f32_e32 v3, v9, v9
	v_fmac_f32_e32 v2, v6, v6
	v_fmac_f32_e32 v3, v8, v8
	v_add_f32_e32 v2, v2, v3
	v_mul_f32_e32 v3, v13, v13
	v_mul_f32_e32 v4, v11, v11
	v_fmac_f32_e32 v3, v12, v12
	v_fmac_f32_e32 v4, v10, v10
	v_add_f32_e32 v3, v3, v4
	v_add_f32_e32 v2, v2, v3
	v_add_f32_e32 v2, v20, v2
	ds_bpermute_b32 v3, v151, v2
	s_waitcnt lgkmcnt(0)
	v_add_f32_e32 v2, v2, v3
	ds_bpermute_b32 v3, v150, v2
	s_and_saveexec_b64 s[10:11], s[38:39]
	s_cbranch_execz .LBB0_271
	v_lshlrev_b64 v[4:5], 7, v[18:19]
	v_lshl_add_u64 v[4:5], s[28:29], 0, v[4:5]
	v_lshl_add_u64 v[4:5], s[8:9], 2, v[4:5]
	s_lshl_b32 s56, s51, 2
	v_lshl_add_u64 v[4:5], v[4:5], 0, s[56:57]
	s_waitcnt lgkmcnt(0)
	v_add_f32_e32 v2, v2, v3
	global_store_dword v[4:5], v2, off

; __device__ __forceinline__ u32x4 pack8(const f32x4 a, const f32x4 b) { u32x4 w; w.x = cvt_pk(a[0], a[1]); w.y = cvt_pk(a[2], a[3]); w.z = cvt_pk(b[0], b[1]); w.w = cvt_pk(b[2], b[3]); return w; }
; __device__ __forceinline__ f32x4 sigm4(f32x4 v) { f32x4 o; o[0] = sigm(v[0]); o[1] = sigm(v[1]); o[2] = sigm(v[2]); o[3] = sigm(v[3]); return o; }
; __device__ __forceinline__ float sq4(f32x4 v) { return (v[0] * v[0] + v[1] * v[1]) + (v[2] * v[2] + v[3] * v[3]); }
; #define EP_ROWLOOP for (int ai = 0; ai < 2; ++ai) _Pragma("unroll") for (int m = 0; m < 4; ++m)
;     __device__ __forceinline__ void operator()(const f32x4 (&acc)[2][2][4][2], const Unit& u, int wr, int wc, int fr, int fq) const {
;     ...
;         EP_ROWLOOP { EpFence fence_{(m & (EPB - 1)) == EPB - 1};
;             const int row = rowb + ai * 128 + m * 16;
;             float rs = 1.0f; if constexpr (MODE == 1) rs = rs_get<32>(rc, ssin, u.pm, wr * 64 + fr + ai * 128 + m * 16, fq, 1.0f / 2048.0f, 1e-6f);
;             float s = 0.f;
; #pragma unroll
;             for (int bj = 0; bj < 2; ++bj) {
;                 const size_t off = (size_t)row * 2048 + cb + bj * 128;
;                 f32x4 v0 = acc[ai][bj][m][0], v1 = acc[ai][bj][m][1], x0, x1;
;                 if constexpr (MODE == 1) { f32x4 e0, e1; unpack8(*(const u32x4*)(e + off), e0, e1); v0 = sigm4(v0 * rs) * e0; v1 = sigm4(v1 * rs) * e1; }
;                 unpack8(*(const u32x4*)(xold + off), x0, x1);
;                 v0 += x0; v1 += x1;
;                 *(u32x4*)(xnew + off) = pack8(v0, v1);
;                 s += sq4(v0) + sq4(v1);
;             }
;             s += __shfl_xor(s, 16); s += __shfl_xor(s, 32);
;             if (fq == 0) ssout[(size_t)row * 32 + u.pn * 4 + wc] = s;
.LBB0_479:
	v_and_b32_e32 v144, 64, v190
	v_xor_b32_e32 v143, 16, v190
	v_add_u32_e32 v144, 64, v144
	v_cmp_lt_i32_e32 vcc, v143, v144
	v_lshl_add_u32 v142, s86, 8, v146
	v_lshl_or_b32 v140, s56, 8, v148
	v_cndmask_b32_e32 v143, v190, v143, vcc
	s_waitcnt vmcnt(0)
	v_lshlrev_b32_e32 v151, 2, v143
	v_xor_b32_e32 v143, 32, v190
	v_cmp_lt_i32_e32 vcc, v143, v144
	v_ashrrev_i32_e32 v141, 31, v140
	s_lshl_b32 s8, s56, 2
	v_cndmask_b32_e32 v143, v190, v143, vcc
	v_lshlrev_b32_e32 v150, 2, v143
	v_ashrrev_i32_e32 v143, 31, v142
	v_lshlrev_b64 v[144:145], 11, v[142:143]
	v_lshl_add_u64 v[144:145], v[144:145], 0, v[140:141]
	v_lshlrev_b64 v[144:145], 1, v[144:145]
	v_lshl_add_u64 v[152:153], s[26:27], 0, v[144:145]
	v_mov_b32_e32 v252, v152
	v_mov_b32_e32 v253, v153
	global_load_dwordx4 v[152:155], v[152:153], off
	global_load_dwordx4 v[192:195], v[252:253], off offset:256
	s_mov_b32 s99, 0
	s_mov_b32 s98, 0x10000
	v_lshl_add_u64 v[252:253], v[252:253], 0, s[98:99]
	global_load_dwordx4 v[196:199], v[252:253], off
	global_load_dwordx4 v[200:203], v[252:253], off offset:256
	s_mov_b32 s98, 0x10000
	v_lshl_add_u64 v[252:253], v[252:253], 0, s[98:99]
	global_load_dwordx4 v[204:207], v[252:253], off
	global_load_dwordx4 v[208:211], v[252:253], off offset:256
	s_mov_b32 s98, 0x10000
	v_lshl_add_u64 v[252:253], v[252:253], 0, s[98:99]
	global_load_dwordx4 v[212:215], v[252:253], off
	global_load_dwordx4 v[216:219], v[252:253], off offset:256
	s_mov_b32 s98, 0x50000
	v_lshl_add_u64 v[252:253], v[252:253], 0, s[98:99]
	global_load_dwordx4 v[220:223], v[252:253], off
	global_load_dwordx4 v[224:227], v[252:253], off offset:256
	s_mov_b32 s98, 0x10000
	v_lshl_add_u64 v[252:253], v[252:253], 0, s[98:99]
	global_load_dwordx4 v[228:231], v[252:253], off
	global_load_dwordx4 v[232:235], v[252:253], off offset:256
	s_mov_b32 s98, 0x10000
	v_lshl_add_u64 v[252:253], v[252:253], 0, s[98:99]
	global_load_dwordx4 v[236:239], v[252:253], off
	global_load_dwordx4 v[240:243], v[252:253], off offset:256
	s_mov_b32 s98, 0x10000
	v_lshl_add_u64 v[252:253], v[252:253], 0, s[98:99]
	global_load_dwordx4 v[244:247], v[252:253], off
	global_load_dwordx4 v[248:251], v[252:253], off offset:256
	s_ashr_i32 s9, s8, 31
	s_waitcnt vmcnt(15)
	v_lshlrev_b32_e32 v156, 16, v152
	v_and_b32_e32 v157, 0xffff0000, v152
	v_lshlrev_b32_e32 v152, 16, v153
	v_and_b32_e32 v153, 0xffff0000, v153
	v_lshlrev_b32_e32 v158, 16, v154
	v_and_b32_e32 v159, 0xffff0000, v154
	v_lshlrev_b32_e32 v154, 16, v155
	v_and_b32_e32 v155, 0xffff0000, v155
	v_pk_add_f32 v[152:153], v[124:125], v[152:153]
	v_pk_add_f32 v[156:157], v[122:123], v[156:157]
	v_pk_add_f32 v[128:129], v[128:129], v[154:155]
	v_pk_add_f32 v[126:127], v[126:127], v[158:159]
	v_cvt_pk_bf16_f32 v122, v156, v157
	v_cvt_pk_bf16_f32 v123, v152, v153
	v_cvt_pk_bf16_f32 v124, v126, v127
	v_cvt_pk_bf16_f32 v125, v128, v129
	v_lshl_add_u64 v[154:155], s[28:29], 0, v[144:145]
	global_store_dwordx4 v[154:155], v[122:125], off
	v_or_b32_e32 v144, 0x100, v144
	s_nop 0
	v_mul_f32_e32 v122, v157, v157
	v_mul_f32_e32 v123, v153, v153
	v_fmac_f32_e32 v122, v156, v156
	v_fmac_f32_e32 v123, v152, v152
	v_add_f32_e32 v122, v122, v123
	v_mul_f32_e32 v123, v127, v127
	v_mul_f32_e32 v124, v129, v129
	v_fmac_f32_e32 v123, v126, v126
	v_fmac_f32_e32 v124, v128, v128
	v_add_f32_e32 v123, v123, v124
	v_add_f32_e32 v152, v122, v123
	v_lshl_add_u64 v[122:123], s[26:27], 0, v[144:145]
	s_waitcnt vmcnt(15)
	v_mov_b32_e32 v122, v192
	v_mov_b32_e32 v123, v193
	v_mov_b32_e32 v124, v194
	v_mov_b32_e32 v125, v195
	v_lshlrev_b32_e32 v126, 16, v122
	v_and_b32_e32 v127, 0xffff0000, v122
	v_lshlrev_b32_e32 v122, 16, v123
	v_and_b32_e32 v123, 0xffff0000, v123
	v_lshlrev_b32_e32 v128, 16, v124
	v_and_b32_e32 v129, 0xffff0000, v124
	v_lshlrev_b32_e32 v124, 16, v125
	v_and_b32_e32 v125, 0xffff0000, v125
	v_pk_add_f32 v[120:121], v[120:121], v[122:123]
	v_pk_add_f32 v[118:119], v[118:119], v[126:127]
	v_pk_add_f32 v[122:123], v[116:117], v[124:125]
	v_pk_add_f32 v[124:125], v[114:115], v[128:129]
	v_cvt_pk_bf16_f32 v114, v118, v119
	v_cvt_pk_bf16_f32 v115, v120, v121
	v_cvt_pk_bf16_f32 v116, v124, v125
	v_cvt_pk_bf16_f32 v117, v122, v123
	v_lshl_add_u64 v[126:127], s[28:29], 0, v[144:145]
	global_store_dwordx4 v[126:127], v[114:117], off
	s_nop 1
	v_mul_f32_e32 v114, v119, v119
	v_mul_f32_e32 v115, v121, v121
	v_fmac_f32_e32 v114, v118, v118
	v_fmac_f32_e32 v115, v120, v120
	v_add_f32_e32 v114, v114, v115
	v_mul_f32_e32 v115, v125, v125
	v_mul_f32_e32 v116, v123, v123
	v_fmac_f32_e32 v115, v124, v124
	v_fmac_f32_e32 v116, v122, v122
	v_add_f32_e32 v115, v115, v116
	v_add_f32_e32 v114, v114, v115
	v_add_f32_e32 v114, v152, v114
	ds_bpermute_b32 v115, v151, v114
	s_waitcnt lgkmcnt(0)
	v_add_f32_e32 v114, v114, v115
	ds_bpermute_b32 v115, v150, v114
	s_and_saveexec_b64 s[10:11], s[38:39]
	s_cbranch_execz .LBB0_481
	v_lshlrev_b64 v[116:117], 7, v[142:143]
	v_lshl_add_u64 v[116:117], s[30:31], 0, v[116:117]
	v_lshl_add_u64 v[116:117], s[8:9], 2, v[116:117]
	s_lshl_b32 s56, s75, 2
	v_lshl_add_u64 v[116:117], v[116:117], 0, s[56:57]
	s_waitcnt lgkmcnt(0)
	v_add_f32_e32 v114, v114, v115
	global_store_dword v[116:117], v114, off
; __device__ __forceinline__ u32x4 pack8(const f32x4 a, const f32x4 b) { u32x4 w; w.x = cvt_pk(a[0], a[1]); w.y = cvt_pk(a[2], a[3]); w.z = cvt_pk(b[0], b[1]); w.w = cvt_pk(b[2], b[3]); return w; }
; __device__ __forceinline__ f32x4 sigm4(f32x4 v) { f32x4 o; o[0] = sigm(v[0]); o[1] = sigm(v[1]); o[2] = sigm(v[2]); o[3] = sigm(v[3]); return o; }
; __device__ __forceinline__ float sq4(f32x4 v) { return (v[0] * v[0] + v[1] * v[1]) + (v[2] * v[2] + v[3] * v[3]); }
; #define EP_ROWLOOP for (int ai = 0; ai < 2; ++ai) _Pragma("unroll") for (int m = 0; m < 4; ++m)
;     __device__ __forceinline__ void operator()(const f32x4 (&acc)[2][2][4][2], const Unit& u, int wr, int wc, int fr, int fq) const {
;     ...
;         EP_ROWLOOP { EpFence fence_{(m & (EPB - 1)) == EPB - 1};
;             const int row = rowb + ai * 128 + m * 16;
;             float rs = 1.0f; if constexpr (MODE == 1) rs = rs_get<32>(rc, ssin, u.pm, wr * 64 + fr + ai * 128 + m * 16, fq, 1.0f / 2048.0f, 1e-6f);
;             float s = 0.f;
; #pragma unroll
;             for (int bj = 0; bj < 2; ++bj) {
;                 const size_t off = (size_t)row * 2048 + cb + bj * 128;
;                 f32x4 v0 = acc[ai][bj][m][0], v1 = acc[ai][bj][m][1], x0, x1;
;                 if constexpr (MODE == 1) { f32x4 e0, e1; unpack8(*(const u32x4*)(e + off), e0, e1); v0 = sigm4(v0 * rs) * e0; v1 = sigm4(v1 * rs) * e1; }
;                 unpack8(*(const u32x4*)(xold + off), x0, x1);
;                 v0 += x0; v1 += x1;
;                 *(u32x4*)(xnew + off) = pack8(v0, v1);
;                 s += sq4(v0) + sq4(v1);
;             }
;             s += __shfl_xor(s, 16); s += __shfl_xor(s, 32);
;             if (fq == 0) ssout[(size_t)row * 32 + u.pn * 4 + wc] = s;
.LBB0_481:
	s_or_b64 exec, exec, s[10:11]
	v_or_b32_e32 v114, 16, v142
	s_waitcnt lgkmcnt(0)
	v_ashrrev_i32_e32 v115, 31, v114
	v_lshlrev_b64 v[116:117], 11, v[114:115]
	v_lshl_add_u64 v[116:117], v[116:117], 0, v[140:141]
	v_lshlrev_b64 v[116:117], 1, v[116:117]
	v_lshl_add_u64 v[118:119], s[26:27], 0, v[116:117]
	s_waitcnt vmcnt(15)
	v_mov_b32_e32 v118, v196
	v_mov_b32_e32 v119, v197
	v_mov_b32_e32 v120, v198
	v_mov_b32_e32 v121, v199
	v_lshlrev_b32_e32 v122, 16, v118
	v_and_b32_e32 v123, 0xffff0000, v118
	v_lshlrev_b32_e32 v118, 16, v119
	v_and_b32_e32 v119, 0xffff0000, v119
	v_lshlrev_b32_e32 v124, 16, v120
	v_and_b32_e32 v125, 0xffff0000, v120
	v_lshlrev_b32_e32 v120, 16, v121
	v_and_b32_e32 v121, 0xffff0000, v121
	v_pk_add_f32 v[112:113], v[112:113], v[118:119]
	v_pk_add_f32 v[110:111], v[110:111], v[122:123]
	v_pk_add_f32 v[118:119], v[108:109], v[120:121]
	v_pk_add_f32 v[120:121], v[106:107], v[124:125]
	v_cvt_pk_bf16_f32 v106, v110, v111
	v_cvt_pk_bf16_f32 v107, v112, v113
	v_cvt_pk_bf16_f32 v108, v120, v121
	v_cvt_pk_bf16_f32 v109, v118, v119
	v_lshl_add_u64 v[122:123], s[28:29], 0, v[116:117]
	global_store_dwordx4 v[122:123], v[106:109], off
	v_or_b32_e32 v116, 0x100, v116
	s_nop 0
	v_mul_f32_e32 v106, v111, v111
	v_mul_f32_e32 v107, v113, v113
	v_fmac_f32_e32 v106, v110, v110
	v_fmac_f32_e32 v107, v112, v112
	v_add_f32_e32 v106, v106, v107
	v_mul_f32_e32 v107, v121, v121
	v_mul_f32_e32 v108, v119, v119
	v_fmac_f32_e32 v107, v120, v120
	v_fmac_f32_e32 v108, v118, v118
	v_add_f32_e32 v107, v107, v108
	v_add_f32_e32 v118, v106, v107
	v_lshl_add_u64 v[106:107], s[26:27], 0, v[116:117]
	s_waitcnt vmcnt(15)
	v_mov_b32_e32 v106, v200
	v_mov_b32_e32 v107, v201
	v_mov_b32_e32 v108, v202
	v_mov_b32_e32 v109, v203
	v_lshlrev_b32_e32 v110, 16, v106
	v_and_b32_e32 v111, 0xffff0000, v106
	v_lshlrev_b32_e32 v106, 16, v107
	v_and_b32_e32 v107, 0xffff0000, v107
	v_lshlrev_b32_e32 v112, 16, v108
	v_and_b32_e32 v113, 0xffff0000, v108
	v_lshlrev_b32_e32 v108, 16, v109
	v_and_b32_e32 v109, 0xffff0000, v109
	v_pk_add_f32 v[104:105], v[104:105], v[106:107]
	v_pk_add_f32 v[102:103], v[102:103], v[110:111]
	v_pk_add_f32 v[106:107], v[100:101], v[108:109]
	v_pk_add_f32 v[108:109], v[98:99], v[112:113]
	v_cvt_pk_bf16_f32 v98, v102, v103
	v_cvt_pk_bf16_f32 v99, v104, v105
	v_cvt_pk_bf16_f32 v100, v108, v109
	v_cvt_pk_bf16_f32 v101, v106, v107
	v_lshl_add_u64 v[110:111], s[28:29], 0, v[116:117]
	global_store_dwordx4 v[110:111], v[98:101], off
	s_nop 1
	v_mul_f32_e32 v98, v103, v103
	v_mul_f32_e32 v99, v105, v105
	v_fmac_f32_e32 v98, v102, v102
	v_fmac_f32_e32 v99, v104, v104
	v_add_f32_e32 v98, v98, v99
	v_mul_f32_e32 v99, v109, v109
	v_mul_f32_e32 v100, v107, v107
	v_fmac_f32_e32 v99, v108, v108
	v_fmac_f32_e32 v100, v106, v106
	v_add_f32_e32 v99, v99, v100
	v_add_f32_e32 v98, v98, v99
	v_add_f32_e32 v98, v118, v98
	ds_bpermute_b32 v99, v151, v98
	s_waitcnt lgkmcnt(0)
	v_add_f32_e32 v98, v98, v99
	ds_bpermute_b32 v99, v150, v98
	s_and_saveexec_b64 s[10:11], s[38:39]
	s_cbranch_execz .LBB0_483
	v_lshlrev_b64 v[100:101], 7, v[114:115]
	v_lshl_add_u64 v[100:101], s[30:31], 0, v[100:101]
	v_lshl_add_u64 v[100:101], s[8:9], 2, v[100:101]
	s_lshl_b32 s56, s75, 2
	v_lshl_add_u64 v[100:101], v[100:101], 0, s[56:57]
	s_waitcnt lgkmcnt(0)
	v_add_f32_e32 v98, v98, v99
	global_store_dword v[100:101], v98, off
.LBB0_483:
	s_or_b64 exec, exec, s[10:11]
	v_or_b32_e32 v98, 32, v142
	s_waitcnt lgkmcnt(0)
	v_ashrrev_i32_e32 v99, 31, v98
	v_lshlrev_b64 v[100:101], 11, v[98:99]
	v_lshl_add_u64 v[100:101], v[100:101], 0, v[140:141]
	v_lshlrev_b64 v[100:101], 1, v[100:101]
	v_lshl_add_u64 v[102:103], s[26:27], 0, v[100:101]
	s_waitcnt vmcnt(15)
	v_mov_b32_e32 v102, v204
	v_mov_b32_e32 v103, v205
	v_mov_b32_e32 v104, v206
	v_mov_b32_e32 v105, v207
	v_lshlrev_b32_e32 v106, 16, v102
	v_and_b32_e32 v107, 0xffff0000, v102
	v_lshlrev_b32_e32 v102, 16, v103
	v_and_b32_e32 v103, 0xffff0000, v103
	v_lshlrev_b32_e32 v108, 16, v104
	v_and_b32_e32 v109, 0xffff0000, v104
	v_lshlrev_b32_e32 v104, 16, v105
	v_and_b32_e32 v105, 0xffff0000, v105
	v_pk_add_f32 v[96:97], v[96:97], v[102:103]
	v_pk_add_f32 v[94:95], v[94:95], v[106:107]
	v_pk_add_f32 v[102:103], v[92:93], v[104:105]
	v_pk_add_f32 v[104:105], v[90:91], v[108:109]
	v_cvt_pk_bf16_f32 v90, v94, v95
	v_cvt_pk_bf16_f32 v91, v96, v97
	v_cvt_pk_bf16_f32 v92, v104, v105
	v_cvt_pk_bf16_f32 v93, v102, v103
	v_lshl_add_u64 v[106:107], s[28:29], 0, v[100:101]
	global_store_dwordx4 v[106:107], v[90:93], off
	v_or_b32_e32 v100, 0x100, v100
	s_nop 0
	v_mul_f32_e32 v90, v95, v95
	v_mul_f32_e32 v91, v97, v97
	v_fmac_f32_e32 v90, v94, v94
	v_fmac_f32_e32 v91, v96, v96
	v_add_f32_e32 v90, v90, v91
	v_mul_f32_e32 v91, v105, v105
	v_mul_f32_e32 v92, v103, v103
	v_fmac_f32_e32 v91, v104, v104
	v_fmac_f32_e32 v92, v102, v102
	v_add_f32_e32 v91, v91, v92
	v_add_f32_e32 v102, v90, v91
	v_lshl_add_u64 v[90:91], s[26:27], 0, v[100:101]
	s_waitcnt vmcnt(15)
	v_mov_b32_e32 v90, v208
	v_mov_b32_e32 v91, v209
	v_mov_b32_e32 v92, v210
	v_mov_b32_e32 v93, v211
	v_lshlrev_b32_e32 v94, 16, v90
	v_and_b32_e32 v95, 0xffff0000, v90
	v_lshlrev_b32_e32 v90, 16, v91
	v_and_b32_e32 v91, 0xffff0000, v91
	v_lshlrev_b32_e32 v96, 16, v92
	v_and_b32_e32 v97, 0xffff0000, v92
	v_lshlrev_b32_e32 v92, 16, v93
	v_and_b32_e32 v93, 0xffff0000, v93
	v_pk_add_f32 v[88:89], v[88:89], v[90:91]
	v_pk_add_f32 v[86:87], v[86:87], v[94:95]
	v_pk_add_f32 v[90:91], v[84:85], v[92:93]
	v_pk_add_f32 v[92:93], v[82:83], v[96:97]
	v_cvt_pk_bf16_f32 v82, v86, v87
	v_cvt_pk_bf16_f32 v83, v88, v89
	v_cvt_pk_bf16_f32 v84, v92, v93
	v_cvt_pk_bf16_f32 v85, v90, v91
	v_lshl_add_u64 v[94:95], s[28:29], 0, v[100:101]
	global_store_dwordx4 v[94:95], v[82:85], off
	s_nop 1
	v_mul_f32_e32 v82, v87, v87
	v_mul_f32_e32 v83, v89, v89
	v_fmac_f32_e32 v82, v86, v86
	v_fmac_f32_e32 v83, v88, v88
	v_add_f32_e32 v82, v82, v83
	v_mul_f32_e32 v83, v93, v93
	v_mul_f32_e32 v84, v91, v91
	v_fmac_f32_e32 v83, v92, v92
	v_fmac_f32_e32 v84, v90, v90
	v_add_f32_e32 v83, v83, v84
	v_add_f32_e32 v82, v82, v83
	v_add_f32_e32 v82, v102, v82
	ds_bpermute_b32 v83, v151, v82
	s_waitcnt lgkmcnt(0)
	v_add_f32_e32 v82, v82, v83
	ds_bpermute_b32 v83, v150, v82
	s_and_saveexec_b64 s[10:11], s[38:39]
	s_cbranch_execz .LBB0_485
	v_lshlrev_b64 v[84:85], 7, v[98:99]
	v_lshl_add_u64 v[84:85], s[30:31], 0, v[84:85]
	v_lshl_add_u64 v[84:85], s[8:9], 2, v[84:85]
	s_lshl_b32 s56, s75, 2
	v_lshl_add_u64 v[84:85], v[84:85], 0, s[56:57]
	s_waitcnt lgkmcnt(0)
	v_add_f32_e32 v82, v82, v83
	global_store_dword v[84:85], v82, off
; __device__ __forceinline__ u32x4 pack8(const f32x4 a, const f32x4 b) { u32x4 w; w.x = cvt_pk(a[0], a[1]); w.y = cvt_pk(a[2], a[3]); w.z = cvt_pk(b[0], b[1]); w.w = cvt_pk(b[2], b[3]); return w; }
; __device__ __forceinline__ f32x4 sigm4(f32x4 v) { f32x4 o; o[0] = sigm(v[0]); o[1] = sigm(v[1]); o[2] = sigm(v[2]); o[3] = sigm(v[3]); return o; }
; __device__ __forceinline__ float sq4(f32x4 v) { return (v[0] * v[0] + v[1] * v[1]) + (v[2] * v[2] + v[3] * v[3]); }
; #define EP_ROWLOOP for (int ai = 0; ai < 2; ++ai) _Pragma("unroll") for (int m = 0; m < 4; ++m)
;     __device__ __forceinline__ void operator()(const f32x4 (&acc)[2][2][4][2], const Unit& u, int wr, int wc, int fr, int fq) const {
;     ...
;         EP_ROWLOOP { EpFence fence_{(m & (EPB - 1)) == EPB - 1};
;             const int row = rowb + ai * 128 + m * 16;
;             float rs = 1.0f; if constexpr (MODE == 1) rs = rs_get<32>(rc, ssin, u.pm, wr * 64 + fr + ai * 128 + m * 16, fq, 1.0f / 2048.0f, 1e-6f);
;             float s = 0.f;
; #pragma unroll
;             for (int bj = 0; bj < 2; ++bj) {
;                 const size_t off = (size_t)row * 2048 + cb + bj * 128;
;                 f32x4 v0 = acc[ai][bj][m][0], v1 = acc[ai][bj][m][1], x0, x1;
;                 if constexpr (MODE == 1) { f32x4 e0, e1; unpack8(*(const u32x4*)(e + off), e0, e1); v0 = sigm4(v0 * rs) * e0; v1 = sigm4(v1 * rs) * e1; }
;                 unpack8(*(const u32x4*)(xold + off), x0, x1);
;                 v0 += x0; v1 += x1;
;                 *(u32x4*)(xnew + off) = pack8(v0, v1);
;                 s += sq4(v0) + sq4(v1);
;             }
;             s += __shfl_xor(s, 16); s += __shfl_xor(s, 32);
;             if (fq == 0) ssout[(size_t)row * 32 + u.pn * 4 + wc] = s;
.LBB0_485:
	s_or_b64 exec, exec, s[10:11]
	v_or_b32_e32 v82, 48, v142
	s_waitcnt lgkmcnt(0)
	v_ashrrev_i32_e32 v83, 31, v82
	v_lshlrev_b64 v[84:85], 11, v[82:83]
	v_lshl_add_u64 v[84:85], v[84:85], 0, v[140:141]
	v_lshlrev_b64 v[84:85], 1, v[84:85]
	v_lshl_add_u64 v[86:87], s[26:27], 0, v[84:85]
	s_waitcnt vmcnt(15)
	v_mov_b32_e32 v86, v212
	v_mov_b32_e32 v87, v213
	v_mov_b32_e32 v88, v214
	v_mov_b32_e32 v89, v215
	v_lshlrev_b32_e32 v90, 16, v86
	v_and_b32_e32 v91, 0xffff0000, v86
	v_lshlrev_b32_e32 v86, 16, v87
	v_and_b32_e32 v87, 0xffff0000, v87
	v_lshlrev_b32_e32 v92, 16, v88
	v_and_b32_e32 v93, 0xffff0000, v88
	v_lshlrev_b32_e32 v88, 16, v89
	v_and_b32_e32 v89, 0xffff0000, v89
	v_pk_add_f32 v[80:81], v[80:81], v[86:87]
	v_pk_add_f32 v[78:79], v[78:79], v[90:91]
	v_pk_add_f32 v[86:87], v[76:77], v[88:89]
	v_pk_add_f32 v[88:89], v[74:75], v[92:93]
	v_cvt_pk_bf16_f32 v74, v78, v79
	v_cvt_pk_bf16_f32 v75, v80, v81
	v_cvt_pk_bf16_f32 v76, v88, v89
	v_cvt_pk_bf16_f32 v77, v86, v87
	v_lshl_add_u64 v[90:91], s[28:29], 0, v[84:85]
	global_store_dwordx4 v[90:91], v[74:77], off
	v_or_b32_e32 v84, 0x100, v84
	s_nop 0
	v_mul_f32_e32 v74, v79, v79
	v_mul_f32_e32 v75, v81, v81
	v_fmac_f32_e32 v74, v78, v78
	v_fmac_f32_e32 v75, v80, v80
	v_add_f32_e32 v74, v74, v75
	v_mul_f32_e32 v75, v89, v89
	v_mul_f32_e32 v76, v87, v87
	v_fmac_f32_e32 v75, v88, v88
	v_fmac_f32_e32 v76, v86, v86
	v_add_f32_e32 v75, v75, v76
	v_add_f32_e32 v86, v74, v75
	v_lshl_add_u64 v[74:75], s[26:27], 0, v[84:85]
	s_waitcnt vmcnt(15)
	v_mov_b32_e32 v74, v216
	v_mov_b32_e32 v75, v217
	v_mov_b32_e32 v76, v218
	v_mov_b32_e32 v77, v219
	v_lshlrev_b32_e32 v78, 16, v74
	v_and_b32_e32 v79, 0xffff0000, v74
	v_lshlrev_b32_e32 v74, 16, v75
	v_and_b32_e32 v75, 0xffff0000, v75
	v_lshlrev_b32_e32 v80, 16, v76
	v_and_b32_e32 v81, 0xffff0000, v76
	v_lshlrev_b32_e32 v76, 16, v77
	v_and_b32_e32 v77, 0xffff0000, v77
	v_pk_add_f32 v[72:73], v[72:73], v[74:75]
	v_pk_add_f32 v[70:71], v[70:71], v[78:79]
	v_pk_add_f32 v[74:75], v[68:69], v[76:77]
	v_pk_add_f32 v[76:77], v[66:67], v[80:81]
	v_cvt_pk_bf16_f32 v66, v70, v71
	v_cvt_pk_bf16_f32 v67, v72, v73
	v_cvt_pk_bf16_f32 v68, v76, v77
	v_cvt_pk_bf16_f32 v69, v74, v75
	v_lshl_add_u64 v[78:79], s[28:29], 0, v[84:85]
	global_store_dwordx4 v[78:79], v[66:69], off
	s_nop 1
	v_mul_f32_e32 v66, v71, v71
	v_mul_f32_e32 v67, v73, v73
	v_fmac_f32_e32 v66, v70, v70
	v_fmac_f32_e32 v67, v72, v72
	v_add_f32_e32 v66, v66, v67
	v_mul_f32_e32 v67, v77, v77
	v_mul_f32_e32 v68, v75, v75
	v_fmac_f32_e32 v67, v76, v76
	v_fmac_f32_e32 v68, v74, v74
	v_add_f32_e32 v67, v67, v68
	v_add_f32_e32 v66, v66, v67
	v_add_f32_e32 v66, v86, v66
	ds_bpermute_b32 v67, v151, v66
	s_waitcnt lgkmcnt(0)
	v_add_f32_e32 v66, v66, v67
	ds_bpermute_b32 v67, v150, v66
	s_and_saveexec_b64 s[10:11], s[38:39]
	s_cbranch_execz .LBB0_487
	v_lshlrev_b64 v[68:69], 7, v[82:83]
	v_lshl_add_u64 v[68:69], s[30:31], 0, v[68:69]
	v_lshl_add_u64 v[68:69], s[8:9], 2, v[68:69]
	s_lshl_b32 s56, s75, 2
	v_lshl_add_u64 v[68:69], v[68:69], 0, s[56:57]
	s_waitcnt lgkmcnt(0)
	v_add_f32_e32 v66, v66, v67
	global_store_dword v[68:69], v66, off
.LBB0_487:
	s_or_b64 exec, exec, s[10:11]
	v_add_u32_e32 v66, 0x80, v142
	s_waitcnt lgkmcnt(0)
	v_ashrrev_i32_e32 v67, 31, v66
	v_lshlrev_b64 v[68:69], 11, v[66:67]
	v_lshl_add_u64 v[68:69], v[68:69], 0, v[140:141]
	v_lshlrev_b64 v[68:69], 1, v[68:69]
	v_lshl_add_u64 v[70:71], s[26:27], 0, v[68:69]
	s_waitcnt vmcnt(15)
	v_mov_b32_e32 v70, v220
	v_mov_b32_e32 v71, v221
	v_mov_b32_e32 v72, v222
	v_mov_b32_e32 v73, v223
	v_lshlrev_b32_e32 v74, 16, v70
	v_and_b32_e32 v75, 0xffff0000, v70
	v_lshlrev_b32_e32 v70, 16, v71
	v_and_b32_e32 v71, 0xffff0000, v71
	v_lshlrev_b32_e32 v76, 16, v72
	v_and_b32_e32 v77, 0xffff0000, v72
	v_lshlrev_b32_e32 v72, 16, v73
	v_and_b32_e32 v73, 0xffff0000, v73
	v_pk_add_f32 v[64:65], v[64:65], v[70:71]
	v_pk_add_f32 v[62:63], v[62:63], v[74:75]
	v_pk_add_f32 v[70:71], v[60:61], v[72:73]
	v_pk_add_f32 v[72:73], v[58:59], v[76:77]
	v_cvt_pk_bf16_f32 v58, v62, v63
	v_cvt_pk_bf16_f32 v59, v64, v65
	v_cvt_pk_bf16_f32 v60, v72, v73
	v_cvt_pk_bf16_f32 v61, v70, v71
	v_lshl_add_u64 v[74:75], s[28:29], 0, v[68:69]
	global_store_dwordx4 v[74:75], v[58:61], off
	v_or_b32_e32 v68, 0x100, v68
	s_nop 0
	v_mul_f32_e32 v58, v63, v63
	v_mul_f32_e32 v59, v65, v65
	v_fmac_f32_e32 v58, v62, v62
	v_fmac_f32_e32 v59, v64, v64
	v_add_f32_e32 v58, v58, v59
	v_mul_f32_e32 v59, v73, v73
	v_mul_f32_e32 v60, v71, v71
	v_fmac_f32_e32 v59, v72, v72
	v_fmac_f32_e32 v60, v70, v70
	v_add_f32_e32 v59, v59, v60
	v_add_f32_e32 v70, v58, v59
	v_lshl_add_u64 v[58:59], s[26:27], 0, v[68:69]
	s_waitcnt vmcnt(15)
	v_mov_b32_e32 v58, v224
	v_mov_b32_e32 v59, v225
	v_mov_b32_e32 v60, v226
	v_mov_b32_e32 v61, v227
	v_lshlrev_b32_e32 v62, 16, v58
	v_and_b32_e32 v63, 0xffff0000, v58
	v_lshlrev_b32_e32 v58, 16, v59
	v_and_b32_e32 v59, 0xffff0000, v59
	v_lshlrev_b32_e32 v64, 16, v60
	v_and_b32_e32 v65, 0xffff0000, v60
	v_lshlrev_b32_e32 v60, 16, v61
	v_and_b32_e32 v61, 0xffff0000, v61
	v_pk_add_f32 v[56:57], v[56:57], v[58:59]
	v_pk_add_f32 v[54:55], v[54:55], v[62:63]
	v_pk_add_f32 v[58:59], v[52:53], v[60:61]
	v_pk_add_f32 v[60:61], v[50:51], v[64:65]
	v_cvt_pk_bf16_f32 v50, v54, v55
	v_cvt_pk_bf16_f32 v51, v56, v57
	v_cvt_pk_bf16_f32 v52, v60, v61
	v_cvt_pk_bf16_f32 v53, v58, v59
	v_lshl_add_u64 v[62:63], s[28:29], 0, v[68:69]
	global_store_dwordx4 v[62:63], v[50:53], off
	s_nop 1
	v_mul_f32_e32 v50, v55, v55
	v_mul_f32_e32 v51, v57, v57
	v_fmac_f32_e32 v50, v54, v54
	v_fmac_f32_e32 v51, v56, v56
	v_add_f32_e32 v50, v50, v51
	v_mul_f32_e32 v51, v61, v61
	v_mul_f32_e32 v52, v59, v59
	v_fmac_f32_e32 v51, v60, v60
	v_fmac_f32_e32 v52, v58, v58
	v_add_f32_e32 v51, v51, v52
	v_add_f32_e32 v50, v50, v51
	v_add_f32_e32 v50, v70, v50
	ds_bpermute_b32 v51, v151, v50
	s_waitcnt lgkmcnt(0)
	v_add_f32_e32 v50, v50, v51
	ds_bpermute_b32 v51, v150, v50
	s_and_saveexec_b64 s[10:11], s[38:39]
	s_cbranch_execz .LBB0_489
	v_lshlrev_b64 v[52:53], 7, v[66:67]
	v_lshl_add_u64 v[52:53], s[30:31], 0, v[52:53]
	v_lshl_add_u64 v[52:53], s[8:9], 2, v[52:53]
	s_lshl_b32 s56, s75, 2
	v_lshl_add_u64 v[52:53], v[52:53], 0, s[56:57]
	s_waitcnt lgkmcnt(0)
	v_add_f32_e32 v50, v50, v51
	global_store_dword v[52:53], v50, off
; __device__ __forceinline__ u32x4 pack8(const f32x4 a, const f32x4 b) { u32x4 w; w.x = cvt_pk(a[0], a[1]); w.y = cvt_pk(a[2], a[3]); w.z = cvt_pk(b[0], b[1]); w.w = cvt_pk(b[2], b[3]); return w; }
; __device__ __forceinline__ f32x4 sigm4(f32x4 v) { f32x4 o; o[0] = sigm(v[0]); o[1] = sigm(v[1]); o[2] = sigm(v[2]); o[3] = sigm(v[3]); return o; }
; __device__ __forceinline__ float sq4(f32x4 v) { return (v[0] * v[0] + v[1] * v[1]) + (v[2] * v[2] + v[3] * v[3]); }
; #define EP_ROWLOOP for (int ai = 0; ai < 2; ++ai) _Pragma("unroll") for (int m = 0; m < 4; ++m)
;     __device__ __forceinline__ void operator()(const f32x4 (&acc)[2][2][4][2], const Unit& u, int wr, int wc, int fr, int fq) const {
;     ...
;         EP_ROWLOOP { EpFence fence_{(m & (EPB - 1)) == EPB - 1};
;             const int row = rowb + ai * 128 + m * 16;
;             float rs = 1.0f; if constexpr (MODE == 1) rs = rs_get<32>(rc, ssin, u.pm, wr * 64 + fr + ai * 128 + m * 16, fq, 1.0f / 2048.0f, 1e-6f);
;             float s = 0.f;
; #pragma unroll
;             for (int bj = 0; bj < 2; ++bj) {
;                 const size_t off = (size_t)row * 2048 + cb + bj * 128;
;                 f32x4 v0 = acc[ai][bj][m][0], v1 = acc[ai][bj][m][1], x0, x1;
;                 if constexpr (MODE == 1) { f32x4 e0, e1; unpack8(*(const u32x4*)(e + off), e0, e1); v0 = sigm4(v0 * rs) * e0; v1 = sigm4(v1 * rs) * e1; }
;                 unpack8(*(const u32x4*)(xold + off), x0, x1);
;                 v0 += x0; v1 += x1;
;                 *(u32x4*)(xnew + off) = pack8(v0, v1);
;                 s += sq4(v0) + sq4(v1);
;             }
;             s += __shfl_xor(s, 16); s += __shfl_xor(s, 32);
;             if (fq == 0) ssout[(size_t)row * 32 + u.pn * 4 + wc] = s;
.LBB0_489:
	s_or_b64 exec, exec, s[10:11]
	v_add_u32_e32 v50, 0x90, v142
	s_waitcnt lgkmcnt(0)
	v_ashrrev_i32_e32 v51, 31, v50
	v_lshlrev_b64 v[52:53], 11, v[50:51]
	v_lshl_add_u64 v[52:53], v[52:53], 0, v[140:141]
	v_lshlrev_b64 v[52:53], 1, v[52:53]
	v_lshl_add_u64 v[54:55], s[26:27], 0, v[52:53]
	s_waitcnt vmcnt(15)
	v_mov_b32_e32 v54, v228
	v_mov_b32_e32 v55, v229
	v_mov_b32_e32 v56, v230
	v_mov_b32_e32 v57, v231
	v_lshlrev_b32_e32 v58, 16, v54
	v_and_b32_e32 v59, 0xffff0000, v54
	v_lshlrev_b32_e32 v54, 16, v55
	v_and_b32_e32 v55, 0xffff0000, v55
	v_lshlrev_b32_e32 v60, 16, v56
	v_and_b32_e32 v61, 0xffff0000, v56
	v_lshlrev_b32_e32 v56, 16, v57
	v_and_b32_e32 v57, 0xffff0000, v57
	v_pk_add_f32 v[48:49], v[48:49], v[54:55]
	v_pk_add_f32 v[46:47], v[46:47], v[58:59]
	v_pk_add_f32 v[54:55], v[44:45], v[56:57]
	v_pk_add_f32 v[56:57], v[42:43], v[60:61]
	v_cvt_pk_bf16_f32 v42, v46, v47
	v_cvt_pk_bf16_f32 v43, v48, v49
	v_cvt_pk_bf16_f32 v44, v56, v57
	v_cvt_pk_bf16_f32 v45, v54, v55
	v_lshl_add_u64 v[58:59], s[28:29], 0, v[52:53]
	global_store_dwordx4 v[58:59], v[42:45], off
	v_or_b32_e32 v52, 0x100, v52
	s_nop 0
	v_mul_f32_e32 v42, v47, v47
	v_mul_f32_e32 v43, v49, v49
	v_fmac_f32_e32 v42, v46, v46
	v_fmac_f32_e32 v43, v48, v48
	v_add_f32_e32 v42, v42, v43
	v_mul_f32_e32 v43, v57, v57
	v_mul_f32_e32 v44, v55, v55
	v_fmac_f32_e32 v43, v56, v56
	v_fmac_f32_e32 v44, v54, v54
	v_add_f32_e32 v43, v43, v44
	v_add_f32_e32 v54, v42, v43
	v_lshl_add_u64 v[42:43], s[26:27], 0, v[52:53]
	s_waitcnt vmcnt(15)
	v_mov_b32_e32 v42, v232
	v_mov_b32_e32 v43, v233
	v_mov_b32_e32 v44, v234
	v_mov_b32_e32 v45, v235
	v_lshlrev_b32_e32 v46, 16, v42
	v_and_b32_e32 v47, 0xffff0000, v42
	v_lshlrev_b32_e32 v42, 16, v43
	v_and_b32_e32 v43, 0xffff0000, v43
	v_lshlrev_b32_e32 v48, 16, v44
	v_and_b32_e32 v49, 0xffff0000, v44
	v_lshlrev_b32_e32 v44, 16, v45
	v_and_b32_e32 v45, 0xffff0000, v45
	v_pk_add_f32 v[40:41], v[40:41], v[42:43]
	v_pk_add_f32 v[38:39], v[38:39], v[46:47]
	v_pk_add_f32 v[42:43], v[36:37], v[44:45]
	v_pk_add_f32 v[44:45], v[34:35], v[48:49]
	v_cvt_pk_bf16_f32 v34, v38, v39
	v_cvt_pk_bf16_f32 v35, v40, v41
	v_cvt_pk_bf16_f32 v36, v44, v45
	v_cvt_pk_bf16_f32 v37, v42, v43
	v_lshl_add_u64 v[46:47], s[28:29], 0, v[52:53]
	global_store_dwordx4 v[46:47], v[34:37], off
	s_nop 1
	v_mul_f32_e32 v34, v39, v39
	v_mul_f32_e32 v35, v41, v41
	v_fmac_f32_e32 v34, v38, v38
	v_fmac_f32_e32 v35, v40, v40
	v_add_f32_e32 v34, v34, v35
	v_mul_f32_e32 v35, v45, v45
	v_mul_f32_e32 v36, v43, v43
	v_fmac_f32_e32 v35, v44, v44
	v_fmac_f32_e32 v36, v42, v42
	v_add_f32_e32 v35, v35, v36
	v_add_f32_e32 v34, v34, v35
	v_add_f32_e32 v34, v54, v34
	ds_bpermute_b32 v35, v151, v34
	s_waitcnt lgkmcnt(0)
	v_add_f32_e32 v34, v34, v35
	ds_bpermute_b32 v35, v150, v34
	s_and_saveexec_b64 s[10:11], s[38:39]
	s_cbranch_execz .LBB0_491
	v_lshlrev_b64 v[36:37], 7, v[50:51]
	v_lshl_add_u64 v[36:37], s[30:31], 0, v[36:37]
	v_lshl_add_u64 v[36:37], s[8:9], 2, v[36:37]
	s_lshl_b32 s56, s75, 2
	v_lshl_add_u64 v[36:37], v[36:37], 0, s[56:57]
	s_waitcnt lgkmcnt(0)
	v_add_f32_e32 v34, v34, v35
	global_store_dword v[36:37], v34, off
; __device__ __forceinline__ u32x4 pack8(const f32x4 a, const f32x4 b) { u32x4 w; w.x = cvt_pk(a[0], a[1]); w.y = cvt_pk(a[2], a[3]); w.z = cvt_pk(b[0], b[1]); w.w = cvt_pk(b[2], b[3]); return w; }
; __device__ __forceinline__ f32x4 sigm4(f32x4 v) { f32x4 o; o[0] = sigm(v[0]); o[1] = sigm(v[1]); o[2] = sigm(v[2]); o[3] = sigm(v[3]); return o; }
; __device__ __forceinline__ float sq4(f32x4 v) { return (v[0] * v[0] + v[1] * v[1]) + (v[2] * v[2] + v[3] * v[3]); }
; #define EP_ROWLOOP for (int ai = 0; ai < 2; ++ai) _Pragma("unroll") for (int m = 0; m < 4; ++m)
;     __device__ __forceinline__ void operator()(const f32x4 (&acc)[2][2][4][2], const Unit& u, int wr, int wc, int fr, int fq) const {
;     ...
;         EP_ROWLOOP { EpFence fence_{(m & (EPB - 1)) == EPB - 1};
;             const int row = rowb + ai * 128 + m * 16;
;             float rs = 1.0f; if constexpr (MODE == 1) rs = rs_get<32>(rc, ssin, u.pm, wr * 64 + fr + ai * 128 + m * 16, fq, 1.0f / 2048.0f, 1e-6f);
;             float s = 0.f;
; #pragma unroll
;             for (int bj = 0; bj < 2; ++bj) {
;                 const size_t off = (size_t)row * 2048 + cb + bj * 128;
;                 f32x4 v0 = acc[ai][bj][m][0], v1 = acc[ai][bj][m][1], x0, x1;
;                 if constexpr (MODE == 1) { f32x4 e0, e1; unpack8(*(const u32x4*)(e + off), e0, e1); v0 = sigm4(v0 * rs) * e0; v1 = sigm4(v1 * rs) * e1; }
;                 unpack8(*(const u32x4*)(xold + off), x0, x1);
;                 v0 += x0; v1 += x1;
;                 *(u32x4*)(xnew + off) = pack8(v0, v1);
;                 s += sq4(v0) + sq4(v1);
;             }
;             s += __shfl_xor(s, 16); s += __shfl_xor(s, 32);
;             if (fq == 0) ssout[(size_t)row * 32 + u.pn * 4 + wc] = s;
.LBB0_491:
	s_or_b64 exec, exec, s[10:11]
	v_add_u32_e32 v34, 0xa0, v142
	s_waitcnt lgkmcnt(0)
	v_ashrrev_i32_e32 v35, 31, v34
	v_lshlrev_b64 v[36:37], 11, v[34:35]
	v_lshl_add_u64 v[36:37], v[36:37], 0, v[140:141]
	v_lshlrev_b64 v[36:37], 1, v[36:37]
	v_lshl_add_u64 v[38:39], s[26:27], 0, v[36:37]
	s_waitcnt vmcnt(15)
	v_mov_b32_e32 v38, v236
	v_mov_b32_e32 v39, v237
	v_mov_b32_e32 v40, v238
	v_mov_b32_e32 v41, v239
	v_lshlrev_b32_e32 v42, 16, v38
	v_and_b32_e32 v43, 0xffff0000, v38
	v_lshlrev_b32_e32 v38, 16, v39
	v_and_b32_e32 v39, 0xffff0000, v39
	v_lshlrev_b32_e32 v44, 16, v40
	v_and_b32_e32 v45, 0xffff0000, v40
	v_lshlrev_b32_e32 v40, 16, v41
	v_and_b32_e32 v41, 0xffff0000, v41
	v_pk_add_f32 v[32:33], v[32:33], v[38:39]
	v_pk_add_f32 v[30:31], v[30:31], v[42:43]
	v_pk_add_f32 v[38:39], v[28:29], v[40:41]
	v_pk_add_f32 v[40:41], v[26:27], v[44:45]
	v_cvt_pk_bf16_f32 v26, v30, v31
	v_cvt_pk_bf16_f32 v27, v32, v33
	v_cvt_pk_bf16_f32 v28, v40, v41
	v_cvt_pk_bf16_f32 v29, v38, v39
	v_lshl_add_u64 v[42:43], s[28:29], 0, v[36:37]
	global_store_dwordx4 v[42:43], v[26:29], off
	v_or_b32_e32 v36, 0x100, v36
	s_nop 0
	v_mul_f32_e32 v26, v31, v31
	v_mul_f32_e32 v27, v33, v33
	v_fmac_f32_e32 v26, v30, v30
	v_fmac_f32_e32 v27, v32, v32
	v_add_f32_e32 v26, v26, v27
	v_mul_f32_e32 v27, v41, v41
	v_mul_f32_e32 v28, v39, v39
	v_fmac_f32_e32 v27, v40, v40
	v_fmac_f32_e32 v28, v38, v38
	v_add_f32_e32 v27, v27, v28
	v_add_f32_e32 v38, v26, v27
	v_lshl_add_u64 v[26:27], s[26:27], 0, v[36:37]
	s_waitcnt vmcnt(15)
	v_mov_b32_e32 v26, v240
	v_mov_b32_e32 v27, v241
	v_mov_b32_e32 v28, v242
	v_mov_b32_e32 v29, v243
	v_lshlrev_b32_e32 v30, 16, v26
	v_and_b32_e32 v31, 0xffff0000, v26
	v_lshlrev_b32_e32 v26, 16, v27
	v_and_b32_e32 v27, 0xffff0000, v27
	v_lshlrev_b32_e32 v32, 16, v28
	v_and_b32_e32 v33, 0xffff0000, v28
	v_lshlrev_b32_e32 v28, 16, v29
	v_and_b32_e32 v29, 0xffff0000, v29
	v_pk_add_f32 v[24:25], v[24:25], v[26:27]
	v_pk_add_f32 v[22:23], v[22:23], v[30:31]
	v_pk_add_f32 v[26:27], v[20:21], v[28:29]
	v_pk_add_f32 v[28:29], v[18:19], v[32:33]
	v_cvt_pk_bf16_f32 v18, v22, v23
	v_cvt_pk_bf16_f32 v19, v24, v25
	v_cvt_pk_bf16_f32 v20, v28, v29
	v_cvt_pk_bf16_f32 v21, v26, v27
	v_lshl_add_u64 v[30:31], s[28:29], 0, v[36:37]
	global_store_dwordx4 v[30:31], v[18:21], off
	s_nop 1
	v_mul_f32_e32 v18, v23, v23
	v_mul_f32_e32 v19, v25, v25
	v_fmac_f32_e32 v18, v22, v22
	v_fmac_f32_e32 v19, v24, v24
	v_add_f32_e32 v18, v18, v19
	v_mul_f32_e32 v19, v29, v29
	v_mul_f32_e32 v20, v27, v27
	v_fmac_f32_e32 v19, v28, v28
	v_fmac_f32_e32 v20, v26, v26
	v_add_f32_e32 v19, v19, v20
	v_add_f32_e32 v18, v18, v19
	v_add_f32_e32 v18, v38, v18
	ds_bpermute_b32 v19, v151, v18
	s_waitcnt lgkmcnt(0)
	v_add_f32_e32 v18, v18, v19
	ds_bpermute_b32 v19, v150, v18
	s_and_saveexec_b64 s[10:11], s[38:39]
	s_cbranch_execz .LBB0_493
	v_lshlrev_b64 v[20:21], 7, v[34:35]
	v_lshl_add_u64 v[20:21], s[30:31], 0, v[20:21]
	v_lshl_add_u64 v[20:21], s[8:9], 2, v[20:21]
	s_lshl_b32 s56, s75, 2
	v_lshl_add_u64 v[20:21], v[20:21], 0, s[56:57]
	s_waitcnt lgkmcnt(0)
	v_add_f32_e32 v18, v18, v19
	global_store_dword v[20:21], v18, off
.LBB0_493:
	s_or_b64 exec, exec, s[10:11]
	v_add_u32_e32 v18, 0xb0, v142
	s_waitcnt lgkmcnt(0)
	v_ashrrev_i32_e32 v19, 31, v18
	v_lshlrev_b64 v[20:21], 11, v[18:19]
	v_lshl_add_u64 v[20:21], v[20:21], 0, v[140:141]
	v_lshlrev_b64 v[20:21], 1, v[20:21]
	v_lshl_add_u64 v[22:23], s[26:27], 0, v[20:21]
	s_waitcnt vmcnt(15)
	v_mov_b32_e32 v22, v244
	v_mov_b32_e32 v23, v245
	v_mov_b32_e32 v24, v246
	v_mov_b32_e32 v25, v247
	v_lshlrev_b32_e32 v26, 16, v22
	v_and_b32_e32 v27, 0xffff0000, v22
	v_lshlrev_b32_e32 v22, 16, v23
	v_and_b32_e32 v23, 0xffff0000, v23
	v_lshlrev_b32_e32 v28, 16, v24
	v_and_b32_e32 v29, 0xffff0000, v24
	v_lshlrev_b32_e32 v24, 16, v25
	v_and_b32_e32 v25, 0xffff0000, v25
	v_pk_add_f32 v[16:17], v[16:17], v[22:23]
	v_pk_add_f32 v[14:15], v[14:15], v[26:27]
	v_pk_add_f32 v[22:23], v[12:13], v[24:25]
	v_pk_add_f32 v[24:25], v[10:11], v[28:29]
	v_cvt_pk_bf16_f32 v10, v14, v15
	v_cvt_pk_bf16_f32 v11, v16, v17
	v_cvt_pk_bf16_f32 v12, v24, v25
	v_cvt_pk_bf16_f32 v13, v22, v23
	v_lshl_add_u64 v[26:27], s[28:29], 0, v[20:21]
	global_store_dwordx4 v[26:27], v[10:13], off
	v_or_b32_e32 v20, 0x100, v20
	s_nop 0
	v_mul_f32_e32 v10, v15, v15
	v_mul_f32_e32 v11, v17, v17
	v_fmac_f32_e32 v10, v14, v14
	v_fmac_f32_e32 v11, v16, v16
	v_add_f32_e32 v10, v10, v11
	v_mul_f32_e32 v11, v25, v25
	v_mul_f32_e32 v12, v23, v23
	v_fmac_f32_e32 v11, v24, v24
	v_fmac_f32_e32 v12, v22, v22
	v_add_f32_e32 v11, v11, v12
	v_add_f32_e32 v22, v10, v11
	v_lshl_add_u64 v[10:11], s[26:27], 0, v[20:21]
	s_waitcnt vmcnt(15)
	v_mov_b32_e32 v10, v248
	v_mov_b32_e32 v11, v249
	v_mov_b32_e32 v12, v250
	v_mov_b32_e32 v13, v251
	v_lshlrev_b32_e32 v14, 16, v10
	v_and_b32_e32 v15, 0xffff0000, v10
	v_lshlrev_b32_e32 v10, 16, v11
	v_and_b32_e32 v11, 0xffff0000, v11
	v_lshlrev_b32_e32 v16, 16, v12
	v_and_b32_e32 v17, 0xffff0000, v12
	v_lshlrev_b32_e32 v12, 16, v13
	v_and_b32_e32 v13, 0xffff0000, v13
	v_pk_add_f32 v[8:9], v[8:9], v[10:11]
	v_pk_add_f32 v[6:7], v[6:7], v[14:15]
	v_pk_add_f32 v[10:11], v[4:5], v[12:13]
	v_pk_add_f32 v[12:13], v[2:3], v[16:17]
	v_cvt_pk_bf16_f32 v2, v6, v7
	v_cvt_pk_bf16_f32 v3, v8, v9
	v_cvt_pk_bf16_f32 v4, v12, v13
	v_cvt_pk_bf16_f32 v5, v10, v11
	v_lshl_add_u64 v[14:15], s[28:29], 0, v[20:21]
	global_store_dwordx4 v[14:15], v[2:5], off
	s_nop 1
	v_mul_f32_e32 v2, v7, v7
	v_mul_f32_e32 v3, v9, v9
	v_fmac_f32_e32 v2, v6, v6
	v_fmac_f32_e32 v3, v8, v8
	v_add_f32_e32 v2, v2, v3
	v_mul_f32_e32 v3, v13, v13
	v_mul_f32_e32 v4, v11, v11
	v_fmac_f32_e32 v3, v12, v12
	v_fmac_f32_e32 v4, v10, v10
	v_add_f32_e32 v3, v3, v4
	v_add_f32_e32 v2, v2, v3
	v_add_f32_e32 v2, v22, v2
	ds_bpermute_b32 v3, v151, v2
	s_waitcnt lgkmcnt(0)
	v_add_f32_e32 v2, v2, v3
	ds_bpermute_b32 v3, v150, v2
	s_and_saveexec_b64 s[10:11], s[38:39]
	s_cbranch_execz .LBB0_495
	v_lshlrev_b64 v[4:5], 7, v[18:19]
	v_lshl_add_u64 v[4:5], s[30:31], 0, v[4:5]
	v_lshl_add_u64 v[4:5], s[8:9], 2, v[4:5]
	s_lshl_b32 s56, s75, 2
	v_lshl_add_u64 v[4:5], v[4:5], 0, s[56:57]
	s_waitcnt lgkmcnt(0)
	v_add_f32_e32 v2, v2, v3
	global_store_dword v[4:5], v2, off
